# mixer: as v58 (v-tile pair loads + merged preamble) with the 16 ymix stores of the pooling and gating mixers marked non-temporal (every mixer stream is streaming)
# speedup vs baseline: 1.0135x; 1.0135x over previous
; #define LAS __attribute__((address_space(3)))
; __device__ __forceinline__ unsigned pk2(float lo, float hi) { return f2bf(lo) | (f2bf(hi) << 16); }
; __device__ __forceinline__ float bflo(unsigned w) { return __uint_as_float(w << 16); }
; __device__ __forceinline__ float bfhi(unsigned w) { return __uint_as_float(w & 0xffff0000u); }
; __device__ __forceinline__ void pool_item(LAS unsigned char* wl, const bf16* proj, bf16* ymix, const bf16* WpT, const float* pscale, int chunk, int g, int rq, int lane, v4u (&raw)[12], int nxt_it) {
;     ...
;         for (int k = 1; k < win; ++k) { const v4u v = *(const LAS v4u*)(wl + (8 * q + 16 - k) * PP + r * 16);
;             s8[0] += bflo(v.x); s8[1] += bfhi(v.x); s8[2] += bflo(v.y); s8[3] += bfhi(v.y); s8[4] += bflo(v.z); s8[5] += bfhi(v.z); s8[6] += bflo(v.w); s8[7] += bfhi(v.w); }
; #pragma unroll
;         for (int i = 0; i < 8; ++i) { const int t = 8 * q + i;
;             const v4u cur = *(const LAS v4u*)(wl + (t + 16) * PP + r * 16);
;             s8[0] += bflo(cur.x); s8[1] += bfhi(cur.x); s8[2] += bflo(cur.y); s8[3] += bfhi(cur.y); s8[4] += bflo(cur.z); s8[5] += bfhi(cur.z); s8[6] += bflo(cur.w); s8[7] += bfhi(cur.w);
;             const int cnt = min(tseq + t + 1, win); const float inv = 1.0f / (float)cnt;
;             dv[i].x = pk2(s8[0] * inv - bflo(cur.x), s8[1] * inv - bfhi(cur.x)); dv[i].y = pk2(s8[2] * inv - bflo(cur.y), s8[3] * inv - bfhi(cur.y));
;             dv[i].z = pk2(s8[4] * inv - bflo(cur.z), s8[5] * inv - bfhi(cur.z)); dv[i].w = pk2(s8[6] * inv - bflo(cur.w), s8[7] * inv - bfhi(cur.w));
;             const v4u old = *(const LAS v4u*)(wl + (t + 16 - (win - 1)) * PP + r * 16);
;             s8[0] -= bflo(old.x); s8[1] -= bfhi(old.x); s8[2] -= bflo(old.y); s8[3] -= bfhi(old.y); s8[4] -= bflo(old.z); s8[5] -= bfhi(old.z); s8[6] -= bflo(old.w); s8[7] -= bfhi(old.w); }
.LBB0_506:
	ds_read_b128 v[58:61], v56
	s_add_i32 s4, s4, -1
	v_add_u32_e32 v56, 0xfffffef0, v56
	s_cmp_lg_u32 s4, 0
	s_waitcnt lgkmcnt(0)
	v_lshlrev_b32_e32 v63, 16, v59
	v_lshlrev_b32_e32 v62, 16, v58
	v_and_b32_e32 v59, 0xffff0000, v59
	v_and_b32_e32 v58, 0xffff0000, v58
	v_pk_add_f32 v[52:53], v[52:53], v[58:59]
	v_lshlrev_b32_e32 v59, 16, v61
	v_lshlrev_b32_e32 v58, 16, v60
	v_and_b32_e32 v61, 0xffff0000, v61
	v_and_b32_e32 v60, 0xffff0000, v60
	v_pk_add_f32 v[54:55], v[54:55], v[62:63]
	v_pk_add_f32 v[48:49], v[48:49], v[58:59]
	v_pk_add_f32 v[50:51], v[50:51], v[60:61]
	s_cbranch_scc1 .LBB0_506
	s_ashr_i32 s4, s22, 4
	s_ashr_i32 s5, s4, 31
	s_lshl_b32 s11, s22, 5
	s_lshl_b64 s[4:5], s[4:5], 7
	s_and_b32 s11, s11, 0x60
	ds_read_b128 v[56:59], v103 offset:4352
	s_or_b32 s4, s4, s11
	s_ashr_i32 s11, s22, 10
	s_and_b32 s23, s4, 0x1fe0
	s_mul_hi_i32 s22, s11, 0x1c00000
	s_mul_i32 s11, s11, 0x1c00000
	s_add_u32 s11, s13, s11
	s_addc_u32 s22, s14, s22
	s_or_b32 s23, s23, 1
	s_waitcnt lgkmcnt(0)
	v_lshlrev_b32_e32 v68, 16, v58
	v_and_b32_e32 v70, 0xffff0000, v58
	v_or_b32_e32 v58, s23, v104
	v_min_u32_e32 v58, s10, v58
	v_cvt_f32_ubyte0_e32 v58, v58
	v_lshlrev_b32_e32 v69, 16, v59
	v_and_b32_e32 v71, 0xffff0000, v59
	v_div_scale_f32 v59, s[24:25], v58, v58, 1.0
	v_rcp_f32_e32 v60, v59
	v_add_u32_e32 v73, s23, v106
	v_min_u32_e32 v73, s10, v73
	v_cvt_f32_ubyte0_e32 v73, v73
	v_fma_f32 v61, -v59, v60, 1.0
	v_fmac_f32_e32 v60, v61, v60
	v_div_scale_f32 v61, vcc, 1.0, v58, 1.0
	v_mul_f32_e32 v62, v61, v60
	v_div_scale_f32 v74, s[24:25], v73, v73, 1.0
	v_fma_f32 v63, -v59, v62, v61
	v_rcp_f32_e32 v75, v74
	v_fmac_f32_e32 v62, v63, v60
	v_fma_f32 v59, -v59, v62, v61
	v_div_fmas_f32 v59, v59, v60, v62
	v_div_fixup_f32 v72, v59, v58, 1.0
	v_subrev_u32_e32 v58, s10, v104
	s_movk_i32 s8, 0x110
	v_fma_f32 v76, -v74, v75, 1.0
	v_mad_i32_i24 v58, v58, s8, v95
	v_fmac_f32_e32 v75, v76, v75
	v_div_scale_f32 v76, vcc, 1.0, v73, 1.0
	ds_read_b128 v[58:61], v58 offset:4624
	ds_read_b128 v[62:65], v105 offset:4352
	v_mul_f32_e32 v77, v76, v75
	v_fma_f32 v78, -v74, v77, v76
	v_lshlrev_b32_e32 v66, 16, v56
	v_and_b32_e32 v56, 0xffff0000, v56
	v_lshlrev_b32_e32 v67, 16, v57
	v_and_b32_e32 v57, 0xffff0000, v57
	v_fmac_f32_e32 v77, v78, v75
	v_fma_f32 v74, -v74, v77, v76
	v_pk_add_f32 v[52:53], v[52:53], v[56:57]
	v_div_fmas_f32 v74, v74, v75, v77
	v_pk_add_f32 v[54:55], v[54:55], v[66:67]
	v_pk_fma_f32 v[76:77], v[72:73], v[52:53], v[56:57] op_sel_hi:[0,1,1] neg_lo:[0,0,1] neg_hi:[0,0,1]
	s_waitcnt lgkmcnt(0)
	v_lshlrev_b32_e32 v57, 16, v59
	v_lshlrev_b32_e32 v56, 16, v58
	v_pk_fma_f32 v[66:67], v[72:73], v[54:55], v[66:67] op_sel_hi:[0,1,1] neg_lo:[0,0,1] neg_hi:[0,0,1]
	v_pk_add_f32 v[54:55], v[54:55], v[56:57] neg_lo:[0,1] neg_hi:[0,1]
	v_and_b32_e32 v57, 0xffff0000, v59
	v_and_b32_e32 v56, 0xffff0000, v58
	v_pk_add_f32 v[52:53], v[52:53], v[56:57] neg_lo:[0,1] neg_hi:[0,1]
	v_lshlrev_b32_e32 v57, 16, v63
	v_lshlrev_b32_e32 v56, 16, v62
	v_div_fixup_f32 v74, v74, v73, 1.0
	v_pk_add_f32 v[58:59], v[54:55], v[56:57]
	v_and_b32_e32 v55, 0xffff0000, v63
	v_and_b32_e32 v54, 0xffff0000, v62
	v_pk_add_f32 v[62:63], v[52:53], v[54:55]
	v_pk_fma_f32 v[52:53], v[74:75], v[58:59], v[56:57] op_sel_hi:[0,1,1] neg_lo:[0,0,1] neg_hi:[0,0,1]
	v_pk_add_f32 v[48:49], v[48:49], v[68:69]
	v_lshlrev_b32_e32 v57, 16, v61
	v_lshlrev_b32_e32 v56, 16, v60
	v_pk_add_f32 v[50:51], v[50:51], v[70:71]
	v_pk_fma_f32 v[68:69], v[72:73], v[48:49], v[68:69] op_sel_hi:[0,1,1] neg_lo:[0,0,1] neg_hi:[0,0,1]
	v_pk_add_f32 v[48:49], v[48:49], v[56:57] neg_lo:[0,1] neg_hi:[0,1]
	v_and_b32_e32 v57, 0xffff0000, v61
	v_and_b32_e32 v56, 0xffff0000, v60
	v_pk_fma_f32 v[70:71], v[72:73], v[50:51], v[70:71] op_sel_hi:[0,1,1] neg_lo:[0,0,1] neg_hi:[0,0,1]
	v_pk_add_f32 v[50:51], v[50:51], v[56:57] neg_lo:[0,1] neg_hi:[0,1]
	v_lshlrev_b32_e32 v73, 16, v65
	v_lshlrev_b32_e32 v72, 16, v64
	v_and_b32_e32 v65, 0xffff0000, v65
	v_and_b32_e32 v64, 0xffff0000, v64
	v_pk_add_f32 v[56:57], v[48:49], v[72:73]
	v_pk_add_f32 v[60:61], v[50:51], v[64:65]
	v_bfe_u32 v48, v71, 16, 1
	v_bfe_u32 v49, v70, 16, 1
	v_bfe_u32 v50, v77, 16, 1
	v_bfe_u32 v51, v76, 16, 1
	v_pk_fma_f32 v[54:55], v[74:75], v[62:63], v[54:55] op_sel_hi:[0,1,1] neg_lo:[0,0,1] neg_hi:[0,0,1]
	v_add3_u32 v75, v76, v51, s68
	v_add3_u32 v76, v77, v50, s68
	v_add3_u32 v49, v70, v49, s68
	v_add3_u32 v48, v71, v48, s68
	v_bfe_u32 v50, v66, 16, 1
	v_bfe_u32 v51, v67, 16, 1
	v_bfe_u32 v70, v68, 16, 1
	v_bfe_u32 v71, v69, 16, 1
	v_add3_u32 v69, v69, v71, s68
	v_add3_u32 v68, v68, v70, s68
	v_add3_u32 v51, v67, v51, s68
	v_add3_u32 v50, v66, v50, s68
	v_lshrrev_b32_e32 v66, 16, v50
	v_lshrrev_b32_e32 v67, 16, v51
	v_lshrrev_b32_e32 v50, 16, v68
	v_lshrrev_b32_e32 v51, 16, v69
	v_pk_fma_f32 v[64:65], v[74:75], v[60:61], v[64:65] op_sel_hi:[0,1,1] neg_lo:[0,0,1] neg_hi:[0,0,1]
	v_and_or_b32 v51, v48, s37, v51
	v_and_or_b32 v50, v49, s37, v50
	v_and_or_b32 v49, v76, s37, v67
	v_and_or_b32 v48, v75, s37, v66
	v_pk_fma_f32 v[66:67], v[74:75], v[56:57], v[72:73] op_sel_hi:[0,1,1] neg_lo:[0,0,1] neg_hi:[0,0,1]
	v_bfe_u32 v68, v65, 16, 1
	v_bfe_u32 v70, v55, 16, 1
	v_bfe_u32 v69, v64, 16, 1
	v_bfe_u32 v71, v54, 16, 1
	v_add3_u32 v70, v55, v70, s68
	v_add3_u32 v55, v65, v68, s68
	v_bfe_u32 v68, v66, 16, 1
	v_add3_u32 v71, v54, v71, s68
	v_add3_u32 v54, v64, v69, s68
	v_bfe_u32 v64, v52, 16, 1
	v_add3_u32 v66, v66, v68, s68
	v_bfe_u32 v69, v67, 16, 1
	v_add3_u32 v52, v52, v64, s68
	v_lshrrev_b32_e32 v64, 16, v66
	v_bfe_u32 v65, v53, 16, 1
	v_add3_u32 v67, v67, v69, s68
	v_and_or_b32 v54, v54, s37, v64
	v_subrev_u32_e32 v64, s10, v106
	v_add3_u32 v53, v53, v65, s68
	v_lshrrev_b32_e32 v65, 16, v67
	v_mad_i32_i24 v64, v64, s8, v95
	v_and_or_b32 v55, v55, s37, v65
	ds_read_b128 v[64:67], v64 offset:4624
	ds_read_b128 v[72:75], v105 offset:4624
	v_add_u32_e32 v107, s23, v110
	v_min_u32_e32 v107, s10, v107
	v_cvt_f32_ubyte0_e32 v107, v107
	v_div_scale_f32 v109, s[24:25], v107, v107, 1.0
	s_waitcnt lgkmcnt(0)
; #define LAS __attribute__((address_space(3)))
; __device__ __forceinline__ unsigned pk2(float lo, float hi) { return f2bf(lo) | (f2bf(hi) << 16); }
; __device__ __forceinline__ float bflo(unsigned w) { return __uint_as_float(w << 16); }
; __device__ __forceinline__ float bfhi(unsigned w) { return __uint_as_float(w & 0xffff0000u); }
; __device__ __forceinline__ void pool_item(LAS unsigned char* wl, const bf16* proj, bf16* ymix, const bf16* WpT, const float* pscale, int chunk, int g, int rq, int lane, v4u (&raw)[12], int nxt_it) {
;     ...
;         for (int i = 0; i < 8; ++i) { const int t = 8 * q + i;
;             const v4u cur = *(const LAS v4u*)(wl + (t + 16) * PP + r * 16);
;             s8[0] += bflo(cur.x); s8[1] += bfhi(cur.x); s8[2] += bflo(cur.y); s8[3] += bfhi(cur.y); s8[4] += bflo(cur.z); s8[5] += bfhi(cur.z); s8[6] += bflo(cur.w); s8[7] += bfhi(cur.w);
;             const int cnt = min(tseq + t + 1, win); const float inv = 1.0f / (float)cnt;
;             dv[i].x = pk2(s8[0] * inv - bflo(cur.x), s8[1] * inv - bfhi(cur.x)); dv[i].y = pk2(s8[2] * inv - bflo(cur.y), s8[3] * inv - bfhi(cur.y));
;             dv[i].z = pk2(s8[4] * inv - bflo(cur.z), s8[5] * inv - bfhi(cur.z)); dv[i].w = pk2(s8[6] * inv - bflo(cur.w), s8[7] * inv - bfhi(cur.w));
;             const v4u old = *(const LAS v4u*)(wl + (t + 16 - (win - 1)) * PP + r * 16);
;             s8[0] -= bflo(old.x); s8[1] -= bfhi(old.x); s8[2] -= bflo(old.y); s8[3] -= bfhi(old.y); s8[4] -= bflo(old.z); s8[5] -= bfhi(old.z); s8[6] -= bflo(old.w); s8[7] -= bfhi(old.w); }
	v_lshlrev_b32_e32 v122, 16, v72
	v_and_b32_e32 v124, 0xffff0000, v72
	v_or_b32_e32 v72, s23, v108
	v_min_u32_e32 v72, s10, v72
	v_cvt_f32_ubyte0_e32 v72, v72
	v_lshlrev_b32_e32 v123, 16, v73
	v_and_b32_e32 v125, 0xffff0000, v73
	v_div_scale_f32 v73, s[24:25], v72, v72, 1.0
	v_lshlrev_b32_e32 v126, 16, v74
	v_and_b32_e32 v128, 0xffff0000, v74
	v_rcp_f32_e32 v74, v73
	v_lshlrev_b32_e32 v127, 16, v75
	v_and_b32_e32 v129, 0xffff0000, v75
	v_rcp_f32_e32 v111, v109
	v_fma_f32 v75, -v73, v74, 1.0
	v_fmac_f32_e32 v74, v75, v74
	v_div_scale_f32 v75, vcc, 1.0, v72, 1.0
	v_mul_f32_e32 v76, v75, v74
	v_fma_f32 v77, -v73, v76, v75
	v_fmac_f32_e32 v76, v77, v74
	v_fma_f32 v73, -v73, v76, v75
	v_div_fmas_f32 v73, v73, v74, v76
	v_div_fixup_f32 v130, v73, v72, 1.0
	v_subrev_u32_e32 v72, s10, v108
	v_mad_i32_i24 v72, v72, s8, v95
	ds_read_b128 v[72:75], v72 offset:4624
	ds_read_b128 v[76:79], v105 offset:4896
	v_fma_f32 v113, -v109, v111, 1.0
	v_lshrrev_b32_e32 v52, 16, v52
	v_lshrrev_b32_e32 v53, 16, v53
	v_lshlrev_b32_e32 v69, 16, v65
	v_lshlrev_b32_e32 v68, 16, v64
	v_fmac_f32_e32 v111, v113, v111
	v_div_scale_f32 v113, vcc, 1.0, v107, 1.0
	v_and_or_b32 v53, v70, s37, v53
	v_and_or_b32 v52, v71, s37, v52
	v_and_b32_e32 v71, 0xffff0000, v65
	v_and_b32_e32 v70, 0xffff0000, v64
	v_mul_f32_e32 v115, v113, v111
	v_pk_add_f32 v[58:59], v[58:59], v[68:69] neg_lo:[0,1] neg_hi:[0,1]
	v_fma_f32 v117, -v109, v115, v113
	v_pk_add_f32 v[62:63], v[62:63], v[70:71] neg_lo:[0,1] neg_hi:[0,1]
	v_pk_add_f32 v[58:59], v[58:59], v[122:123]
	v_fmac_f32_e32 v115, v117, v111
	v_pk_add_f32 v[62:63], v[62:63], v[124:125]
	v_pk_fma_f32 v[68:69], v[130:131], v[58:59], v[122:123] op_sel_hi:[0,1,1] neg_lo:[0,0,1] neg_hi:[0,0,1]
	s_waitcnt lgkmcnt(0)
	v_lshlrev_b32_e32 v123, 16, v73
	v_lshlrev_b32_e32 v122, 16, v72
	v_and_b32_e32 v73, 0xffff0000, v73
	v_and_b32_e32 v72, 0xffff0000, v72
	v_fma_f32 v109, -v109, v115, v113
	v_pk_fma_f32 v[70:71], v[130:131], v[62:63], v[124:125] op_sel_hi:[0,1,1] neg_lo:[0,0,1] neg_hi:[0,0,1]
	v_pk_add_f32 v[58:59], v[58:59], v[122:123] neg_lo:[0,1] neg_hi:[0,1]
	v_pk_add_f32 v[62:63], v[62:63], v[72:73] neg_lo:[0,1] neg_hi:[0,1]
	v_lshlrev_b32_e32 v73, 16, v77
	v_lshlrev_b32_e32 v72, 16, v76
	v_lshlrev_b32_e32 v65, 16, v67
	v_lshlrev_b32_e32 v64, 16, v66
	v_div_fmas_f32 v109, v109, v111, v115
	v_pk_add_f32 v[122:123], v[58:59], v[72:73]
	v_and_b32_e32 v59, 0xffff0000, v77
	v_and_b32_e32 v58, 0xffff0000, v76
	v_and_b32_e32 v67, 0xffff0000, v67
	v_and_b32_e32 v66, 0xffff0000, v66
	v_div_fixup_f32 v132, v109, v107, 1.0
	v_pk_add_f32 v[76:77], v[62:63], v[58:59]
	v_pk_add_f32 v[56:57], v[56:57], v[64:65] neg_lo:[0,1] neg_hi:[0,1]
	v_pk_fma_f32 v[62:63], v[132:133], v[122:123], v[72:73] op_sel_hi:[0,1,1] neg_lo:[0,0,1] neg_hi:[0,0,1]
	v_pk_fma_f32 v[72:73], v[132:133], v[76:77], v[58:59] op_sel_hi:[0,1,1] neg_lo:[0,0,1] neg_hi:[0,0,1]
	v_pk_add_f32 v[58:59], v[60:61], v[66:67] neg_lo:[0,1] neg_hi:[0,1]
	v_pk_add_f32 v[56:57], v[56:57], v[126:127]
	v_lshlrev_b32_e32 v67, 16, v75
	v_lshlrev_b32_e32 v66, 16, v74
	v_pk_add_f32 v[58:59], v[58:59], v[128:129]
	v_pk_fma_f32 v[60:61], v[130:131], v[56:57], v[126:127] op_sel_hi:[0,1,1] neg_lo:[0,0,1] neg_hi:[0,0,1]
	v_pk_add_f32 v[56:57], v[56:57], v[66:67] neg_lo:[0,1] neg_hi:[0,1]
	v_and_b32_e32 v67, 0xffff0000, v75
	v_and_b32_e32 v66, 0xffff0000, v74
	v_pk_fma_f32 v[64:65], v[130:131], v[58:59], v[128:129] op_sel_hi:[0,1,1] neg_lo:[0,0,1] neg_hi:[0,0,1]
	v_pk_add_f32 v[58:59], v[58:59], v[66:67] neg_lo:[0,1] neg_hi:[0,1]
	v_lshlrev_b32_e32 v67, 16, v79
	v_lshlrev_b32_e32 v66, 16, v78
	v_and_b32_e32 v79, 0xffff0000, v79
	v_and_b32_e32 v78, 0xffff0000, v78
	v_pk_add_f32 v[74:75], v[56:57], v[66:67]
	v_pk_add_f32 v[124:125], v[58:59], v[78:79]
	v_bfe_u32 v56, v65, 16, 1
	v_bfe_u32 v57, v64, 16, 1
	v_bfe_u32 v58, v71, 16, 1
	v_bfe_u32 v59, v70, 16, 1
	v_add3_u32 v70, v70, v59, s68
	v_add3_u32 v71, v71, v58, s68
	v_add3_u32 v57, v64, v57, s68
	v_add3_u32 v56, v65, v56, s68
	v_bfe_u32 v58, v68, 16, 1
	v_bfe_u32 v59, v69, 16, 1
	v_bfe_u32 v64, v60, 16, 1
	v_bfe_u32 v65, v61, 16, 1
	v_add3_u32 v61, v61, v65, s68
	v_add3_u32 v60, v60, v64, s68
	v_add3_u32 v59, v69, v59, s68
	v_add3_u32 v58, v68, v58, s68
	v_lshrrev_b32_e32 v64, 16, v58
	v_lshrrev_b32_e32 v65, 16, v59
	v_lshrrev_b32_e32 v58, 16, v60
	v_lshrrev_b32_e32 v59, 16, v61
	v_and_or_b32 v59, v56, s37, v59
	v_and_or_b32 v58, v57, s37, v58
	v_and_or_b32 v57, v71, s37, v65
	v_and_or_b32 v56, v70, s37, v64
	v_pk_fma_f32 v[60:61], v[132:133], v[74:75], v[66:67] op_sel_hi:[0,1,1] neg_lo:[0,0,1] neg_hi:[0,0,1]
	v_pk_fma_f32 v[64:65], v[132:133], v[124:125], v[78:79] op_sel_hi:[0,1,1] neg_lo:[0,0,1] neg_hi:[0,0,1]
	v_bfe_u32 v66, v65, 16, 1
	v_bfe_u32 v70, v60, 16, 1
	v_bfe_u32 v67, v64, 16, 1
	v_add3_u32 v65, v65, v66, s68
	v_bfe_u32 v66, v62, 16, 1
	v_add3_u32 v60, v60, v70, s68
	v_add3_u32 v64, v64, v67, s68
	v_bfe_u32 v67, v63, 16, 1
	v_bfe_u32 v71, v61, 16, 1
	v_add3_u32 v62, v62, v66, s68
	v_lshrrev_b32_e32 v60, 16, v60
	v_bfe_u32 v68, v73, 16, 1
	v_bfe_u32 v69, v72, 16, 1
	v_add3_u32 v61, v61, v71, s68
	v_add3_u32 v63, v63, v67, s68
	v_lshrrev_b32_e32 v66, 16, v62
	v_and_or_b32 v62, v64, s37, v60
	v_subrev_u32_e32 v64, s10, v110
	v_add3_u32 v69, v72, v69, s68
	v_add3_u32 v68, v73, v68, s68
	v_lshrrev_b32_e32 v67, 16, v63
	v_lshrrev_b32_e32 v61, 16, v61
	v_mad_i32_i24 v64, v64, s8, v95
	v_and_or_b32 v63, v65, s37, v61
	v_and_or_b32 v61, v68, s37, v67
	v_and_or_b32 v60, v69, s37, v66
	ds_read_b128 v[64:67], v64 offset:4624
	v_add_u32_e32 v107, s23, v114
	v_min_u32_e32 v107, s10, v107
	v_cvt_f32_ubyte0_e32 v107, v107
	v_div_scale_f32 v109, s[24:25], v107, v107, 1.0
	s_waitcnt lgkmcnt(0)
; #define LAS __attribute__((address_space(3)))
; __device__ __forceinline__ unsigned pk2(float lo, float hi) { return f2bf(lo) | (f2bf(hi) << 16); }
; __device__ __forceinline__ float bflo(unsigned w) { return __uint_as_float(w << 16); }
; __device__ __forceinline__ float bfhi(unsigned w) { return __uint_as_float(w & 0xffff0000u); }
; __device__ __forceinline__ void pool_item(LAS unsigned char* wl, const bf16* proj, bf16* ymix, const bf16* WpT, const float* pscale, int chunk, int g, int rq, int lane, v4u (&raw)[12], int nxt_it) {
;     ...
;         for (int i = 0; i < 8; ++i) { const int t = 8 * q + i;
;             const v4u cur = *(const LAS v4u*)(wl + (t + 16) * PP + r * 16);
;             s8[0] += bflo(cur.x); s8[1] += bfhi(cur.x); s8[2] += bflo(cur.y); s8[3] += bfhi(cur.y); s8[4] += bflo(cur.z); s8[5] += bfhi(cur.z); s8[6] += bflo(cur.w); s8[7] += bfhi(cur.w);
;             const int cnt = min(tseq + t + 1, win); const float inv = 1.0f / (float)cnt;
;             dv[i].x = pk2(s8[0] * inv - bflo(cur.x), s8[1] * inv - bfhi(cur.x)); dv[i].y = pk2(s8[2] * inv - bflo(cur.y), s8[3] * inv - bfhi(cur.y));
;             dv[i].z = pk2(s8[4] * inv - bflo(cur.z), s8[5] * inv - bfhi(cur.z)); dv[i].w = pk2(s8[6] * inv - bflo(cur.w), s8[7] * inv - bfhi(cur.w));
;             const v4u old = *(const LAS v4u*)(wl + (t + 16 - (win - 1)) * PP + r * 16);
;             s8[0] -= bflo(old.x); s8[1] -= bfhi(old.x); s8[2] -= bflo(old.y); s8[3] -= bfhi(old.y); s8[4] -= bflo(old.z); s8[5] -= bfhi(old.z); s8[6] -= bflo(old.w); s8[7] -= bfhi(old.w); }
	v_lshlrev_b32_e32 v73, 16, v65
	v_lshlrev_b32_e32 v72, 16, v64
	v_and_b32_e32 v79, 0xffff0000, v65
	v_and_b32_e32 v78, 0xffff0000, v64
	v_lshlrev_b32_e32 v131, 16, v67
	v_lshlrev_b32_e32 v130, 16, v66
	v_and_b32_e32 v133, 0xffff0000, v67
	v_and_b32_e32 v132, 0xffff0000, v66
	ds_read_b128 v[64:67], v105 offset:5168
	v_rcp_f32_e32 v111, v109
	v_pk_add_f32 v[76:77], v[76:77], v[78:79] neg_lo:[0,1] neg_hi:[0,1]
	v_pk_add_f32 v[72:73], v[122:123], v[72:73] neg_lo:[0,1] neg_hi:[0,1]
	s_lshl_b32 s6, s6, 8
	s_waitcnt lgkmcnt(0)
	v_lshlrev_b32_e32 v126, 16, v64
	v_and_b32_e32 v128, 0xffff0000, v64
	v_or_b32_e32 v64, s23, v112
	v_min_u32_e32 v64, s10, v64
	v_cvt_f32_ubyte0_e32 v64, v64
	v_lshlrev_b32_e32 v127, 16, v65
	v_and_b32_e32 v129, 0xffff0000, v65
	v_div_scale_f32 v65, s[24:25], v64, v64, 1.0
	v_lshlrev_b32_e32 v134, 16, v66
	v_and_b32_e32 v136, 0xffff0000, v66
	v_rcp_f32_e32 v66, v65
	v_lshlrev_b32_e32 v135, 16, v67
	v_and_b32_e32 v137, 0xffff0000, v67
	v_fma_f32 v113, -v109, v111, 1.0
	v_fma_f32 v67, -v65, v66, 1.0
	v_fmac_f32_e32 v66, v67, v66
	v_div_scale_f32 v67, vcc, 1.0, v64, 1.0
	v_mul_f32_e32 v68, v67, v66
	v_fma_f32 v69, -v65, v68, v67
	v_fmac_f32_e32 v68, v69, v66
	v_fma_f32 v65, -v65, v68, v67
	v_div_fmas_f32 v65, v65, v66, v68
	v_div_fixup_f32 v138, v65, v64, 1.0
	v_subrev_u32_e32 v64, s10, v112
	v_mad_i32_i24 v64, v64, s8, v95
	ds_read_b128 v[64:67], v64 offset:4624
	ds_read_b128 v[68:71], v105 offset:5440
	v_fmac_f32_e32 v111, v113, v111
	v_div_scale_f32 v113, vcc, 1.0, v107, 1.0
	v_mul_f32_e32 v115, v113, v111
	v_fma_f32 v117, -v109, v115, v113
	v_pk_add_f32 v[76:77], v[76:77], v[128:129]
	s_waitcnt lgkmcnt(0)
	v_lshlrev_b32_e32 v123, 16, v65
	v_lshlrev_b32_e32 v122, 16, v64
	v_and_b32_e32 v65, 0xffff0000, v65
	v_and_b32_e32 v64, 0xffff0000, v64
	v_fmac_f32_e32 v115, v117, v111
	v_pk_fma_f32 v[144:145], v[138:139], v[76:77], v[128:129] op_sel_hi:[0,1,1] neg_lo:[0,0,1] neg_hi:[0,0,1]
	v_pk_add_f32 v[64:65], v[76:77], v[64:65] neg_lo:[0,1] neg_hi:[0,1]
	v_lshlrev_b32_e32 v77, 16, v69
	v_lshlrev_b32_e32 v76, 16, v68
	v_and_b32_e32 v69, 0xffff0000, v69
	v_and_b32_e32 v68, 0xffff0000, v68
	v_fma_f32 v109, -v109, v115, v113
	v_pk_add_f32 v[72:73], v[72:73], v[126:127]
	v_pk_add_f32 v[128:129], v[64:65], v[68:69]
	v_pk_add_f32 v[64:65], v[74:75], v[130:131] neg_lo:[0,1] neg_hi:[0,1]
	v_pk_add_f32 v[74:75], v[124:125], v[132:133] neg_lo:[0,1] neg_hi:[0,1]
	v_div_fmas_f32 v109, v109, v111, v115
	v_pk_fma_f32 v[78:79], v[138:139], v[72:73], v[126:127] op_sel_hi:[0,1,1] neg_lo:[0,0,1] neg_hi:[0,0,1]
	v_pk_add_f32 v[72:73], v[72:73], v[122:123] neg_lo:[0,1] neg_hi:[0,1]
	v_pk_add_f32 v[74:75], v[74:75], v[136:137]
	v_lshlrev_b32_e32 v123, 16, v67
	v_lshlrev_b32_e32 v122, 16, v66
	v_and_b32_e32 v67, 0xffff0000, v67
	v_and_b32_e32 v66, 0xffff0000, v66
	v_div_fixup_f32 v142, v109, v107, 1.0
	v_pk_add_f32 v[126:127], v[72:73], v[76:77]
	v_pk_add_f32 v[64:65], v[64:65], v[134:135]
	v_pk_fma_f32 v[130:131], v[138:139], v[74:75], v[136:137] op_sel_hi:[0,1,1] neg_lo:[0,0,1] neg_hi:[0,0,1]
	v_pk_add_f32 v[66:67], v[74:75], v[66:67] neg_lo:[0,1] neg_hi:[0,1]
	v_lshlrev_b32_e32 v75, 16, v71
	v_lshlrev_b32_e32 v74, 16, v70
	v_and_b32_e32 v71, 0xffff0000, v71
	v_and_b32_e32 v70, 0xffff0000, v70
	v_pk_fma_f32 v[72:73], v[142:143], v[126:127], v[76:77] op_sel_hi:[0,1,1] neg_lo:[0,0,1] neg_hi:[0,0,1]
	v_pk_fma_f32 v[76:77], v[138:139], v[64:65], v[134:135] op_sel_hi:[0,1,1] neg_lo:[0,0,1] neg_hi:[0,0,1]
	v_pk_add_f32 v[124:125], v[66:67], v[70:71]
	v_bfe_u32 v66, v145, 16, 1
	v_bfe_u32 v67, v144, 16, 1
	v_add3_u32 v109, v145, v66, s68
	v_bfe_u32 v66, v78, 16, 1
	v_bfe_u32 v111, v76, 16, 1
	v_pk_add_f32 v[64:65], v[64:65], v[122:123] neg_lo:[0,1] neg_hi:[0,1]
	v_add3_u32 v107, v144, v67, s68
	v_bfe_u32 v67, v79, 16, 1
	v_bfe_u32 v113, v77, 16, 1
	v_add3_u32 v76, v76, v111, s68
	v_add3_u32 v66, v78, v66, s68
	v_pk_fma_f32 v[70:71], v[142:143], v[124:125], v[70:71] op_sel_hi:[0,1,1] neg_lo:[0,0,1] neg_hi:[0,0,1]
	v_pk_add_f32 v[122:123], v[64:65], v[74:75]
	v_bfe_u32 v64, v131, 16, 1
	v_bfe_u32 v65, v130, 16, 1
	v_add3_u32 v77, v77, v113, s68
	v_add3_u32 v67, v79, v67, s68
	v_lshrrev_b32_e32 v78, 16, v66
	v_lshrrev_b32_e32 v66, 16, v76
	v_bfe_u32 v76, v71, 16, 1
	v_pk_fma_f32 v[68:69], v[142:143], v[128:129], v[68:69] op_sel_hi:[0,1,1] neg_lo:[0,0,1] neg_hi:[0,0,1]
	v_add3_u32 v65, v130, v65, s68
	v_add3_u32 v64, v131, v64, s68
	v_lshrrev_b32_e32 v79, 16, v67
	v_lshrrev_b32_e32 v67, 16, v77
	v_add3_u32 v71, v71, v76, s68
	v_bfe_u32 v76, v72, 16, 1
	v_and_or_b32 v67, v64, s37, v67
	v_and_or_b32 v66, v65, s37, v66
	v_and_or_b32 v65, v109, s37, v79
	v_and_or_b32 v64, v107, s37, v78
	v_pk_fma_f32 v[74:75], v[142:143], v[122:123], v[74:75] op_sel_hi:[0,1,1] neg_lo:[0,0,1] neg_hi:[0,0,1]
	v_bfe_u32 v77, v70, 16, 1
	v_bfe_u32 v78, v69, 16, 1
	v_bfe_u32 v79, v68, 16, 1
	v_add3_u32 v72, v72, v76, s68
	v_add3_u32 v68, v68, v79, s68
	v_add3_u32 v69, v69, v78, s68
	v_add3_u32 v70, v70, v77, s68
	v_bfe_u32 v77, v73, 16, 1
	v_bfe_u32 v78, v74, 16, 1
	v_bfe_u32 v79, v75, 16, 1
	v_lshrrev_b32_e32 v72, 16, v72
	v_add3_u32 v75, v75, v79, s68
	v_add3_u32 v74, v74, v78, s68
	v_add3_u32 v73, v73, v77, s68
	v_and_or_b32 v68, v68, s37, v72
	v_subrev_u32_e32 v72, s10, v114
	v_lshrrev_b32_e32 v73, 16, v73
	v_lshrrev_b32_e32 v74, 16, v74
	v_lshrrev_b32_e32 v75, 16, v75
	v_mad_i32_i24 v72, v72, s8, v95
	v_and_or_b32 v71, v71, s37, v75
	v_and_or_b32 v70, v70, s37, v74
	v_and_or_b32 v69, v69, s37, v73
	ds_read_b128 v[72:75], v72 offset:4624
	v_add_u32_e32 v107, s23, v118
	v_min_u32_e32 v107, s10, v107
	v_cvt_f32_ubyte0_e32 v107, v107
	v_div_scale_f32 v109, s[24:25], v107, v107, 1.0
	s_waitcnt lgkmcnt(0)
; #define LAS __attribute__((address_space(3)))
; __device__ __forceinline__ unsigned pk2(float lo, float hi) { return f2bf(lo) | (f2bf(hi) << 16); }
; __device__ __forceinline__ float bflo(unsigned w) { return __uint_as_float(w << 16); }
; __device__ __forceinline__ float bfhi(unsigned w) { return __uint_as_float(w & 0xffff0000u); }
; __device__ __forceinline__ void pool_item(LAS unsigned char* wl, const bf16* proj, bf16* ymix, const bf16* WpT, const float* pscale, int chunk, int g, int rq, int lane, v4u (&raw)[12], int nxt_it) {
;     ...
;         for (int i = 0; i < 8; ++i) { const int t = 8 * q + i;
;             const v4u cur = *(const LAS v4u*)(wl + (t + 16) * PP + r * 16);
;             s8[0] += bflo(cur.x); s8[1] += bfhi(cur.x); s8[2] += bflo(cur.y); s8[3] += bfhi(cur.y); s8[4] += bflo(cur.z); s8[5] += bfhi(cur.z); s8[6] += bflo(cur.w); s8[7] += bfhi(cur.w);
;             const int cnt = min(tseq + t + 1, win); const float inv = 1.0f / (float)cnt;
;             dv[i].x = pk2(s8[0] * inv - bflo(cur.x), s8[1] * inv - bfhi(cur.x)); dv[i].y = pk2(s8[2] * inv - bflo(cur.y), s8[3] * inv - bfhi(cur.y));
;             dv[i].z = pk2(s8[4] * inv - bflo(cur.z), s8[5] * inv - bfhi(cur.z)); dv[i].w = pk2(s8[6] * inv - bflo(cur.w), s8[7] * inv - bfhi(cur.w));
;             const v4u old = *(const LAS v4u*)(wl + (t + 16 - (win - 1)) * PP + r * 16);
;             s8[0] -= bflo(old.x); s8[1] -= bfhi(old.x); s8[2] -= bflo(old.y); s8[3] -= bfhi(old.y); s8[4] -= bflo(old.z); s8[5] -= bfhi(old.z); s8[6] -= bflo(old.w); s8[7] -= bfhi(old.w); }
	v_lshlrev_b32_e32 v147, 16, v73
	v_lshlrev_b32_e32 v146, 16, v72
	v_and_b32_e32 v149, 0xffff0000, v73
	v_and_b32_e32 v148, 0xffff0000, v72
	v_lshlrev_b32_e32 v131, 16, v75
	v_lshlrev_b32_e32 v130, 16, v74
	v_and_b32_e32 v133, 0xffff0000, v75
	v_and_b32_e32 v132, 0xffff0000, v74
	ds_read_b128 v[72:75], v105 offset:5712
	v_rcp_f32_e32 v111, v109
	v_pk_add_f32 v[128:129], v[128:129], v[148:149] neg_lo:[0,1] neg_hi:[0,1]
	v_pk_add_f32 v[126:127], v[126:127], v[146:147] neg_lo:[0,1] neg_hi:[0,1]
	v_mov_b32_e32 v121, v193
	s_waitcnt lgkmcnt(0)
	v_lshlrev_b32_e32 v144, 16, v72
	v_and_b32_e32 v142, 0xffff0000, v72
	v_or_b32_e32 v72, s23, v116
	v_min_u32_e32 v72, s10, v72
	v_cvt_f32_ubyte0_e32 v72, v72
	v_lshlrev_b32_e32 v145, 16, v73
	v_and_b32_e32 v143, 0xffff0000, v73
	v_div_scale_f32 v73, s[24:25], v72, v72, 1.0
	v_lshlrev_b32_e32 v136, 16, v74
	v_and_b32_e32 v134, 0xffff0000, v74
	v_rcp_f32_e32 v74, v73
	v_lshlrev_b32_e32 v137, 16, v75
	v_and_b32_e32 v135, 0xffff0000, v75
	v_fma_f32 v113, -v109, v111, 1.0
	v_fma_f32 v75, -v73, v74, 1.0
	v_fmac_f32_e32 v74, v75, v74
	v_div_scale_f32 v75, vcc, 1.0, v72, 1.0
	v_mul_f32_e32 v76, v75, v74
	v_fma_f32 v77, -v73, v76, v75
	v_fmac_f32_e32 v76, v77, v74
	v_fma_f32 v73, -v73, v76, v75
	v_div_fmas_f32 v73, v73, v74, v76
	v_div_fixup_f32 v138, v73, v72, 1.0
	v_subrev_u32_e32 v72, s10, v116
	v_mad_i32_i24 v72, v72, s8, v95
	ds_read_b128 v[72:75], v72 offset:4624
	ds_read_b128 v[76:79], v105 offset:5984
	v_fmac_f32_e32 v111, v113, v111
	v_div_scale_f32 v113, vcc, 1.0, v107, 1.0
	v_mul_f32_e32 v115, v113, v111
	v_fma_f32 v117, -v109, v115, v113
	v_fmac_f32_e32 v115, v117, v111
	v_fma_f32 v109, -v109, v115, v113
	v_pk_add_f32 v[128:129], v[128:129], v[142:143]
	s_waitcnt lgkmcnt(0)
; #define LAS __attribute__((address_space(3)))
; __device__ __forceinline__ unsigned pk2(float lo, float hi) { return f2bf(lo) | (f2bf(hi) << 16); }
; __device__ __forceinline__ float bflo(unsigned w) { return __uint_as_float(w << 16); }
; __device__ __forceinline__ float bfhi(unsigned w) { return __uint_as_float(w & 0xffff0000u); }
; #define LDS_WAIT() asm volatile("s_waitcnt lgkmcnt(0)" ::: "memory")
; __device__ __forceinline__ void pool_item(LAS unsigned char* wl, const bf16* proj, bf16* ymix, const bf16* WpT, const float* pscale, int chunk, int g, int rq, int lane, v4u (&raw)[12], int nxt_it) {
;     ...
;         for (int i = 0; i < 8; ++i) { const int t = 8 * q + i;
;             const v4u cur = *(const LAS v4u*)(wl + (t + 16) * PP + r * 16);
;             s8[0] += bflo(cur.x); s8[1] += bfhi(cur.x); s8[2] += bflo(cur.y); s8[3] += bfhi(cur.y); s8[4] += bflo(cur.z); s8[5] += bfhi(cur.z); s8[6] += bflo(cur.w); s8[7] += bfhi(cur.w);
;             const int cnt = min(tseq + t + 1, win); const float inv = 1.0f / (float)cnt;
;             dv[i].x = pk2(s8[0] * inv - bflo(cur.x), s8[1] * inv - bfhi(cur.x)); dv[i].y = pk2(s8[2] * inv - bflo(cur.y), s8[3] * inv - bfhi(cur.y));
;             dv[i].z = pk2(s8[4] * inv - bflo(cur.z), s8[5] * inv - bfhi(cur.z)); dv[i].w = pk2(s8[6] * inv - bflo(cur.w), s8[7] * inv - bfhi(cur.w));
;             const v4u old = *(const LAS v4u*)(wl + (t + 16 - (win - 1)) * PP + r * 16);
;             s8[0] -= bflo(old.x); s8[1] -= bfhi(old.x); s8[2] -= bflo(old.y); s8[3] -= bfhi(old.y); s8[4] -= bflo(old.z); s8[5] -= bfhi(old.z); s8[6] -= bflo(old.w); s8[7] -= bfhi(old.w); }
;     }
; #pragma unroll
;     for (int i = 0; i < 8; ++i) *(v4u*)(ymix + (R0 + 8 * q + i) * D + g * 128 + r * 8) = dv[i];
;     LDS_WAIT();
	v_lshlrev_b32_e32 v147, 16, v73
	v_lshlrev_b32_e32 v146, 16, v72
	v_and_b32_e32 v73, 0xffff0000, v73
	v_and_b32_e32 v72, 0xffff0000, v72
	v_div_fmas_f32 v109, v109, v111, v115
	v_pk_fma_f32 v[142:143], v[138:139], v[128:129], v[142:143] op_sel_hi:[0,1,1] neg_lo:[0,0,1] neg_hi:[0,0,1]
	v_pk_add_f32 v[72:73], v[128:129], v[72:73] neg_lo:[0,1] neg_hi:[0,1]
	v_lshlrev_b32_e32 v129, 16, v77
	v_lshlrev_b32_e32 v128, 16, v76
	v_and_b32_e32 v77, 0xffff0000, v77
	v_and_b32_e32 v76, 0xffff0000, v76
	v_div_fixup_f32 v150, v109, v107, 1.0
	v_pk_add_f32 v[126:127], v[126:127], v[144:145]
	v_pk_add_f32 v[72:73], v[72:73], v[76:77]
	v_pk_fma_f32 v[144:145], v[138:139], v[126:127], v[144:145] op_sel_hi:[0,1,1] neg_lo:[0,0,1] neg_hi:[0,0,1]
	v_pk_add_f32 v[126:127], v[126:127], v[146:147] neg_lo:[0,1] neg_hi:[0,1]
	v_pk_fma_f32 v[76:77], v[150:151], v[72:73], v[76:77] op_sel_hi:[0,1,1] neg_lo:[0,0,1] neg_hi:[0,0,1]
	v_pk_add_f32 v[72:73], v[122:123], v[130:131] neg_lo:[0,1] neg_hi:[0,1]
	v_pk_add_f32 v[122:123], v[124:125], v[132:133] neg_lo:[0,1] neg_hi:[0,1]
	v_pk_add_f32 v[126:127], v[126:127], v[128:129]
	v_pk_add_f32 v[122:123], v[122:123], v[134:135]
	v_lshlrev_b32_e32 v131, 16, v75
	v_lshlrev_b32_e32 v130, 16, v74
	v_and_b32_e32 v75, 0xffff0000, v75
	v_and_b32_e32 v74, 0xffff0000, v74
	v_pk_fma_f32 v[126:127], v[150:151], v[126:127], v[128:129] op_sel_hi:[0,1,1] neg_lo:[0,0,1] neg_hi:[0,0,1]
	v_pk_add_f32 v[72:73], v[72:73], v[136:137]
	v_pk_fma_f32 v[128:129], v[138:139], v[122:123], v[134:135] op_sel_hi:[0,1,1] neg_lo:[0,0,1] neg_hi:[0,0,1]
	v_pk_add_f32 v[74:75], v[122:123], v[74:75] neg_lo:[0,1] neg_hi:[0,1]
	v_lshlrev_b32_e32 v123, 16, v79
	v_lshlrev_b32_e32 v122, 16, v78
	v_and_b32_e32 v79, 0xffff0000, v79
	v_and_b32_e32 v78, 0xffff0000, v78
	v_pk_fma_f32 v[124:125], v[138:139], v[72:73], v[136:137] op_sel_hi:[0,1,1] neg_lo:[0,0,1] neg_hi:[0,0,1]
	v_pk_add_f32 v[132:133], v[74:75], v[78:79]
	v_bfe_u32 v74, v143, 16, 1
	v_bfe_u32 v75, v142, 16, 1
	v_pk_add_f32 v[72:73], v[72:73], v[130:131] neg_lo:[0,1] neg_hi:[0,1]
	v_add3_u32 v107, v142, v75, s68
	v_add3_u32 v109, v143, v74, s68
	v_bfe_u32 v74, v144, 16, 1
	v_bfe_u32 v75, v145, 16, 1
	v_bfe_u32 v111, v124, 16, 1
	v_bfe_u32 v113, v125, 16, 1
	v_pk_add_f32 v[130:131], v[72:73], v[122:123]
	v_add3_u32 v113, v125, v113, s68
	v_add3_u32 v111, v124, v111, s68
	v_add3_u32 v75, v145, v75, s68
	v_add3_u32 v74, v144, v74, s68
	v_lshrrev_b32_e32 v115, 16, v74
	v_lshrrev_b32_e32 v117, 16, v75
	v_lshrrev_b32_e32 v74, 16, v111
	v_lshrrev_b32_e32 v75, 16, v113
	v_pk_fma_f32 v[122:123], v[150:151], v[130:131], v[122:123] op_sel_hi:[0,1,1] neg_lo:[0,0,1] neg_hi:[0,0,1]
	v_bfe_u32 v111, v77, 16, 1
	v_bfe_u32 v113, v76, 16, 1
	s_add_u32 s10, s11, s6
	v_add3_u32 v76, v76, v113, s68
	v_add3_u32 v77, v77, v111, s68
	v_bfe_u32 v111, v122, 16, 1
	v_bfe_u32 v113, v123, 16, 1
	s_addc_u32 s11, s22, 0
	v_mov_b32_e32 v125, s5
	v_or_b32_e32 v124, s4, v104
	v_add3_u32 v113, v123, v113, s68
	v_add3_u32 v111, v122, v111, s68
	v_lshl_add_u64 v[122:123], s[10:11], 0, v[120:121]
	v_lshlrev_b64 v[124:125], 11, v[124:125]
	v_lshl_add_u64 v[124:125], v[122:123], 0, v[124:125]
	global_store_dwordx4 v[124:125], v[48:51], off nt
	v_bfe_u32 v72, v129, 16, 1
	v_bfe_u32 v73, v128, 16, 1
	v_mov_b32_e32 v49, s5
	v_or_b32_e32 v48, s4, v106
	v_lshlrev_b64 v[48:49], 11, v[48:49]
	v_lshl_add_u64 v[48:49], v[122:123], 0, v[48:49]
	global_store_dwordx4 v[48:49], v[52:55], off nt
	v_mov_b32_e32 v49, s5
	v_or_b32_e32 v48, s4, v108
	v_lshlrev_b64 v[48:49], 11, v[48:49]
	v_lshl_add_u64 v[48:49], v[122:123], 0, v[48:49]
	global_store_dwordx4 v[48:49], v[56:59], off nt
	v_mov_b32_e32 v49, s5
	v_or_b32_e32 v48, s4, v110
	v_lshlrev_b64 v[48:49], 11, v[48:49]
	v_lshl_add_u64 v[48:49], v[122:123], 0, v[48:49]
	global_store_dwordx4 v[48:49], v[60:63], off nt
	v_mov_b32_e32 v49, s5
	v_or_b32_e32 v48, s4, v112
	v_lshlrev_b64 v[48:49], 11, v[48:49]
	v_lshl_add_u64 v[48:49], v[122:123], 0, v[48:49]
	global_store_dwordx4 v[48:49], v[64:67], off nt
	v_mov_b32_e32 v49, s5
	v_or_b32_e32 v48, s4, v114
	v_lshlrev_b64 v[48:49], 11, v[48:49]
	v_lshl_add_u64 v[48:49], v[122:123], 0, v[48:49]
	v_add3_u32 v73, v128, v73, s68
	v_add3_u32 v72, v129, v72, s68
	v_pk_fma_f32 v[78:79], v[150:151], v[132:133], v[78:79] op_sel_hi:[0,1,1] neg_lo:[0,0,1] neg_hi:[0,0,1]
	global_store_dwordx4 v[48:49], v[68:71], off nt
	v_mov_b32_e32 v49, s5
	v_or_b32_e32 v48, s4, v116
	v_and_or_b32 v75, v72, s37, v75
	v_and_or_b32 v74, v73, s37, v74
	v_and_or_b32 v73, v109, s37, v117
	v_and_or_b32 v72, v107, s37, v115
	v_bfe_u32 v107, v79, 16, 1
	v_bfe_u32 v109, v78, 16, 1
	v_lshlrev_b64 v[48:49], 11, v[48:49]
	v_add3_u32 v78, v78, v109, s68
	v_add3_u32 v79, v79, v107, s68
	v_bfe_u32 v107, v126, 16, 1
	v_bfe_u32 v109, v127, 16, 1
	v_lshl_add_u64 v[48:49], v[122:123], 0, v[48:49]
	v_add3_u32 v109, v127, v109, s68
	v_add3_u32 v107, v126, v107, s68
	global_store_dwordx4 v[48:49], v[72:75], off nt
	v_mov_b32_e32 v49, s5
	v_or_b32_e32 v48, s4, v118
	v_lshrrev_b32_e32 v107, 16, v107
	v_lshrrev_b32_e32 v109, 16, v109
	v_lshrrev_b32_e32 v111, 16, v111
	v_lshrrev_b32_e32 v113, 16, v113
	v_lshlrev_b64 v[48:49], 11, v[48:49]
	v_and_or_b32 v79, v79, s37, v113
	v_and_or_b32 v78, v78, s37, v111
	v_and_or_b32 v77, v77, s37, v109
	v_and_or_b32 v76, v76, s37, v107
	v_lshl_add_u64 v[48:49], v[122:123], 0, v[48:49]
	global_store_dwordx4 v[48:49], v[76:79], off nt
	s_waitcnt lgkmcnt(0)
	s_and_b64 vcc, exec, s[0:1]
	s_mov_b32 s22, s15
	s_cbranch_vccz .LBB0_500

; #define LAS __attribute__((address_space(3)))
; __device__ __forceinline__ unsigned pk2(float lo, float hi) { return f2bf(lo) | (f2bf(hi) << 16); }
; __device__ __forceinline__ float bflo(unsigned w) { return __uint_as_float(w << 16); }
; __device__ __forceinline__ float bfhi(unsigned w) { return __uint_as_float(w & 0xffff0000u); }
; __device__ __forceinline__ void sgu_item(LAS unsigned char* wl, const bf16* proj, bf16* ymix, const float* vstat, const float* sgu_g, const bf16* Wm, const float* sgu_b, int chunk, int h, int lane) {
;     ...
;         for (int i = 0; i < 8; ++i) { const int s = rsub + 16 * i; const f32x2 ms = st[s]; const v4u w = raw[i];
;             v2u lo, hi; lo.x = pk2((bflo(w.x) - ms.x) * ms.y * g0[0], (bfhi(w.x) - ms.x) * ms.y * g0[1]); lo.y = pk2((bflo(w.y) - ms.x) * ms.y * g0[2], (bfhi(w.y) - ms.x) * ms.y * g0[3]);
;             hi.x = pk2((bflo(w.z) - ms.x) * ms.y * g1[0], (bfhi(w.z) - ms.x) * ms.y * g1[1]); hi.y = pk2((bflo(w.w) - ms.x) * ms.y * g1[2], (bfhi(w.w) - ms.x) * ms.y * g1[3]);
;             *(LAS v2u*)(wl + s * VP2 + (4 * c16) * 2) = lo; *(LAS v2u*)(wl + s * VP2 + (16 + 4 * c16) * 2) = hi; }
.Lsgu_go:
	v_lshlrev_b32_e32 v117, 16, v119
	v_lshlrev_b32_e32 v116, 16, v118
	v_and_b32_e32 v119, 0xffff0000, v119
	v_and_b32_e32 v118, 0xffff0000, v118
	ds_read_b64 v[122:123], v218 offset:10240
	v_lshl_add_u64 v[178:179], v[178:179], 0, s[88:89]
	s_waitcnt lgkmcnt(0)
	v_pk_add_f32 v[116:117], v[116:117], v[122:123] op_sel_hi:[1,0] neg_lo:[0,1] neg_hi:[0,1]
	s_nop 0
	v_pk_mul_f32 v[124:125], v[122:123], v[116:117] op_sel:[1,0]
	v_pk_add_f32 v[118:119], v[118:119], v[122:123] op_sel_hi:[1,0] neg_lo:[0,1] neg_hi:[0,1]
	s_waitcnt vmcnt(0)
	v_mov_b32_e32 v116, v92
	v_mov_b32_e32 v117, v94
	v_pk_mul_f32 v[124:125], v[116:117], v[124:125]
	v_pk_mul_f32 v[118:119], v[122:123], v[118:119] op_sel:[1,0]
	v_mov_b32_e32 v94, v93
	v_pk_mul_f32 v[92:93], v[94:95], v[118:119]
	v_and_b32_sdwa v118, v125, v245 dst_sel:DWORD dst_unused:UNUSED_PAD src0_sel:WORD_1 src1_sel:DWORD
	v_and_b32_sdwa v119, v124, v245 dst_sel:DWORD dst_unused:UNUSED_PAD src0_sel:WORD_1 src1_sel:DWORD
	v_add3_u32 v124, v124, v119, s68
	v_add3_u32 v118, v125, v118, s68
	v_and_b32_sdwa v119, v93, v245 dst_sel:DWORD dst_unused:UNUSED_PAD src0_sel:WORD_1 src1_sel:DWORD
	v_and_b32_sdwa v125, v92, v245 dst_sel:DWORD dst_unused:UNUSED_PAD src0_sel:WORD_1 src1_sel:DWORD
	v_add3_u32 v93, v93, v119, s68
	v_add3_u32 v92, v92, v125, s68
	v_and_b32_e32 v93, 0xffff0000, v93
	v_and_b32_e32 v92, 0xffff0000, v92
	v_or_b32_sdwa v119, v93, v118 dst_sel:DWORD dst_unused:UNUSED_PAD src0_sel:DWORD src1_sel:WORD_1
	v_or_b32_sdwa v118, v92, v124 dst_sel:DWORD dst_unused:UNUSED_PAD src0_sel:DWORD src1_sel:WORD_1
	v_lshlrev_b32_e32 v93, 16, v121
	v_lshlrev_b32_e32 v92, 16, v120
	v_and_b32_e32 v121, 0xffff0000, v121
	v_and_b32_e32 v120, 0xffff0000, v120
	v_pk_add_f32 v[92:93], v[92:93], v[122:123] op_sel_hi:[1,0] neg_lo:[0,1] neg_hi:[0,1]
	v_pk_add_f32 v[120:121], v[120:121], v[122:123] op_sel_hi:[1,0] neg_lo:[0,1] neg_hi:[0,1]
	v_pk_mul_f32 v[124:125], v[122:123], v[92:93] op_sel:[1,0]
	v_mov_b32_e32 v93, v90
	v_pk_mul_f32 v[120:121], v[122:123], v[120:121] op_sel:[1,0]
	v_mov_b32_e32 v90, v89
	v_mov_b32_e32 v92, v88
	v_pk_mul_f32 v[88:89], v[90:91], v[120:121]
	v_pk_mul_f32 v[124:125], v[92:93], v[124:125]
	v_and_b32_sdwa v122, v89, v245 dst_sel:DWORD dst_unused:UNUSED_PAD src0_sel:WORD_1 src1_sel:DWORD
	v_and_b32_sdwa v123, v88, v245 dst_sel:DWORD dst_unused:UNUSED_PAD src0_sel:WORD_1 src1_sel:DWORD
	v_and_b32_sdwa v120, v125, v245 dst_sel:DWORD dst_unused:UNUSED_PAD src0_sel:WORD_1 src1_sel:DWORD
	v_and_b32_sdwa v121, v124, v245 dst_sel:DWORD dst_unused:UNUSED_PAD src0_sel:WORD_1 src1_sel:DWORD
	v_add3_u32 v89, v89, v122, s68
	v_add3_u32 v88, v88, v123, s68
	v_add3_u32 v121, v124, v121, s68
	v_add3_u32 v120, v125, v120, s68
	v_and_b32_e32 v89, 0xffff0000, v89
	v_and_b32_e32 v88, 0xffff0000, v88
	v_or_b32_sdwa v89, v89, v120 dst_sel:DWORD dst_unused:UNUSED_PAD src0_sel:DWORD src1_sel:WORD_1
	v_or_b32_sdwa v88, v88, v121 dst_sel:DWORD dst_unused:UNUSED_PAD src0_sel:DWORD src1_sel:WORD_1
	ds_write2_b64 v219, v[118:119], v[88:89] offset1:4
	ds_read_b64 v[88:89], v218 offset:10368
	v_lshlrev_b32_e32 v119, 16, v113
	v_lshlrev_b32_e32 v118, 16, v112
	v_and_b32_e32 v113, 0xffff0000, v113
	v_and_b32_e32 v112, 0xffff0000, v112
	s_waitcnt lgkmcnt(0)
	v_pk_add_f32 v[118:119], v[118:119], v[88:89] op_sel_hi:[1,0] neg_lo:[0,1] neg_hi:[0,1]
	v_pk_add_f32 v[112:113], v[112:113], v[88:89] op_sel_hi:[1,0] neg_lo:[0,1] neg_hi:[0,1]
	v_pk_mul_f32 v[118:119], v[88:89], v[118:119] op_sel:[1,0]
	v_pk_mul_f32 v[112:113], v[88:89], v[112:113] op_sel:[1,0]
	v_pk_mul_f32 v[118:119], v[116:117], v[118:119]
	v_pk_mul_f32 v[112:113], v[94:95], v[112:113]
	v_and_b32_sdwa v120, v119, v245 dst_sel:DWORD dst_unused:UNUSED_PAD src0_sel:WORD_1 src1_sel:DWORD
	v_and_b32_sdwa v121, v118, v245 dst_sel:DWORD dst_unused:UNUSED_PAD src0_sel:WORD_1 src1_sel:DWORD
	v_add3_u32 v118, v118, v121, s68
	v_add3_u32 v119, v119, v120, s68
	v_and_b32_sdwa v120, v113, v245 dst_sel:DWORD dst_unused:UNUSED_PAD src0_sel:WORD_1 src1_sel:DWORD
	v_and_b32_sdwa v121, v112, v245 dst_sel:DWORD dst_unused:UNUSED_PAD src0_sel:WORD_1 src1_sel:DWORD
	v_add3_u32 v113, v113, v120, s68
	v_add3_u32 v112, v112, v121, s68
	v_and_b32_e32 v113, 0xffff0000, v113
	v_and_b32_e32 v112, 0xffff0000, v112
	v_or_b32_sdwa v113, v113, v119 dst_sel:DWORD dst_unused:UNUSED_PAD src0_sel:DWORD src1_sel:WORD_1
	v_or_b32_sdwa v112, v112, v118 dst_sel:DWORD dst_unused:UNUSED_PAD src0_sel:DWORD src1_sel:WORD_1
	v_lshlrev_b32_e32 v119, 16, v115
	v_lshlrev_b32_e32 v118, 16, v114
	v_pk_add_f32 v[118:119], v[118:119], v[88:89] op_sel_hi:[1,0] neg_lo:[0,1] neg_hi:[0,1]
	v_and_b32_e32 v115, 0xffff0000, v115
	v_and_b32_e32 v114, 0xffff0000, v114
	v_pk_mul_f32 v[118:119], v[88:89], v[118:119] op_sel:[1,0]
	v_pk_add_f32 v[114:115], v[114:115], v[88:89] op_sel_hi:[1,0] neg_lo:[0,1] neg_hi:[0,1]
	v_pk_mul_f32 v[118:119], v[92:93], v[118:119]
	v_pk_mul_f32 v[88:89], v[88:89], v[114:115] op_sel:[1,0]
	v_and_b32_sdwa v114, v119, v245 dst_sel:DWORD dst_unused:UNUSED_PAD src0_sel:WORD_1 src1_sel:DWORD
	v_pk_mul_f32 v[88:89], v[90:91], v[88:89]
	v_and_b32_sdwa v115, v118, v245 dst_sel:DWORD dst_unused:UNUSED_PAD src0_sel:WORD_1 src1_sel:DWORD
	v_add3_u32 v115, v118, v115, s68
	v_add3_u32 v114, v119, v114, s68
	v_and_b32_sdwa v118, v89, v245 dst_sel:DWORD dst_unused:UNUSED_PAD src0_sel:WORD_1 src1_sel:DWORD
	v_and_b32_sdwa v119, v88, v245 dst_sel:DWORD dst_unused:UNUSED_PAD src0_sel:WORD_1 src1_sel:DWORD
	v_add3_u32 v89, v89, v118, s68
	v_add3_u32 v88, v88, v119, s68
	v_and_b32_e32 v89, 0xffff0000, v89
	v_and_b32_e32 v88, 0xffff0000, v88
	v_or_b32_sdwa v89, v89, v114 dst_sel:DWORD dst_unused:UNUSED_PAD src0_sel:DWORD src1_sel:WORD_1
	v_or_b32_sdwa v88, v88, v115 dst_sel:DWORD dst_unused:UNUSED_PAD src0_sel:DWORD src1_sel:WORD_1
	ds_write2_b64 v219, v[112:113], v[88:89] offset0:160 offset1:164
	ds_read_b64 v[112:113], v218 offset:10496
	v_lshlrev_b32_e32 v89, 16, v109
	v_lshlrev_b32_e32 v88, 16, v108
	v_and_b32_e32 v109, 0xffff0000, v109
	v_and_b32_e32 v108, 0xffff0000, v108
	s_waitcnt lgkmcnt(0)
; #define LAS __attribute__((address_space(3)))
; __device__ __forceinline__ unsigned pk2(float lo, float hi) { return f2bf(lo) | (f2bf(hi) << 16); }
; __device__ __forceinline__ float bflo(unsigned w) { return __uint_as_float(w << 16); }
; __device__ __forceinline__ float bfhi(unsigned w) { return __uint_as_float(w & 0xffff0000u); }
; __device__ __forceinline__ void sgu_item(LAS unsigned char* wl, const bf16* proj, bf16* ymix, const float* vstat, const float* sgu_g, const bf16* Wm, const float* sgu_b, int chunk, int h, int lane) {
;     ...
;         for (int i = 0; i < 8; ++i) { const int s = rsub + 16 * i; const f32x2 ms = st[s]; const v4u w = raw[i];
;             v2u lo, hi; lo.x = pk2((bflo(w.x) - ms.x) * ms.y * g0[0], (bfhi(w.x) - ms.x) * ms.y * g0[1]); lo.y = pk2((bflo(w.y) - ms.x) * ms.y * g0[2], (bfhi(w.y) - ms.x) * ms.y * g0[3]);
;             hi.x = pk2((bflo(w.z) - ms.x) * ms.y * g1[0], (bfhi(w.z) - ms.x) * ms.y * g1[1]); hi.y = pk2((bflo(w.w) - ms.x) * ms.y * g1[2], (bfhi(w.w) - ms.x) * ms.y * g1[3]);
;             *(LAS v2u*)(wl + s * VP2 + (4 * c16) * 2) = lo; *(LAS v2u*)(wl + s * VP2 + (16 + 4 * c16) * 2) = hi; }
	v_pk_add_f32 v[88:89], v[88:89], v[112:113] op_sel_hi:[1,0] neg_lo:[0,1] neg_hi:[0,1]
	v_pk_add_f32 v[108:109], v[108:109], v[112:113] op_sel_hi:[1,0] neg_lo:[0,1] neg_hi:[0,1]
	v_pk_mul_f32 v[88:89], v[112:113], v[88:89] op_sel:[1,0]
	v_pk_mul_f32 v[108:109], v[112:113], v[108:109] op_sel:[1,0]
	v_pk_mul_f32 v[88:89], v[116:117], v[88:89]
	v_pk_mul_f32 v[108:109], v[94:95], v[108:109]
	v_and_b32_sdwa v114, v89, v245 dst_sel:DWORD dst_unused:UNUSED_PAD src0_sel:WORD_1 src1_sel:DWORD
	v_and_b32_sdwa v115, v88, v245 dst_sel:DWORD dst_unused:UNUSED_PAD src0_sel:WORD_1 src1_sel:DWORD
	v_add3_u32 v88, v88, v115, s68
	v_add3_u32 v89, v89, v114, s68
	v_and_b32_sdwa v114, v109, v245 dst_sel:DWORD dst_unused:UNUSED_PAD src0_sel:WORD_1 src1_sel:DWORD
	v_and_b32_sdwa v115, v108, v245 dst_sel:DWORD dst_unused:UNUSED_PAD src0_sel:WORD_1 src1_sel:DWORD
	v_add3_u32 v109, v109, v114, s68
	v_add3_u32 v108, v108, v115, s68
	v_and_b32_e32 v109, 0xffff0000, v109
	v_and_b32_e32 v108, 0xffff0000, v108
	v_or_b32_sdwa v89, v109, v89 dst_sel:DWORD dst_unused:UNUSED_PAD src0_sel:DWORD src1_sel:WORD_1
	v_or_b32_sdwa v88, v108, v88 dst_sel:DWORD dst_unused:UNUSED_PAD src0_sel:DWORD src1_sel:WORD_1
	v_lshlrev_b32_e32 v109, 16, v111
	v_lshlrev_b32_e32 v108, 16, v110
	v_pk_add_f32 v[108:109], v[108:109], v[112:113] op_sel_hi:[1,0] neg_lo:[0,1] neg_hi:[0,1]
	v_and_b32_e32 v111, 0xffff0000, v111
	v_and_b32_e32 v110, 0xffff0000, v110
	v_pk_mul_f32 v[108:109], v[112:113], v[108:109] op_sel:[1,0]
	v_pk_add_f32 v[110:111], v[110:111], v[112:113] op_sel_hi:[1,0] neg_lo:[0,1] neg_hi:[0,1]
	v_pk_mul_f32 v[108:109], v[92:93], v[108:109]
	v_pk_mul_f32 v[110:111], v[112:113], v[110:111] op_sel:[1,0]
	v_and_b32_sdwa v112, v109, v245 dst_sel:DWORD dst_unused:UNUSED_PAD src0_sel:WORD_1 src1_sel:DWORD
	v_pk_mul_f32 v[110:111], v[90:91], v[110:111]
	v_and_b32_sdwa v113, v108, v245 dst_sel:DWORD dst_unused:UNUSED_PAD src0_sel:WORD_1 src1_sel:DWORD
	v_add3_u32 v108, v108, v113, s68
	v_add3_u32 v109, v109, v112, s68
	v_and_b32_sdwa v112, v111, v245 dst_sel:DWORD dst_unused:UNUSED_PAD src0_sel:WORD_1 src1_sel:DWORD
	v_and_b32_sdwa v113, v110, v245 dst_sel:DWORD dst_unused:UNUSED_PAD src0_sel:WORD_1 src1_sel:DWORD
	v_add3_u32 v111, v111, v112, s68
	v_add3_u32 v110, v110, v113, s68
	v_and_b32_e32 v111, 0xffff0000, v111
	v_and_b32_e32 v110, 0xffff0000, v110
	v_or_b32_sdwa v109, v111, v109 dst_sel:DWORD dst_unused:UNUSED_PAD src0_sel:DWORD src1_sel:WORD_1
	v_or_b32_sdwa v108, v110, v108 dst_sel:DWORD dst_unused:UNUSED_PAD src0_sel:DWORD src1_sel:WORD_1
	v_add_u32_e32 v110, 0x800, v219
	ds_write2_b64 v110, v[88:89], v[108:109] offset0:64 offset1:68
	ds_read_b64 v[88:89], v218 offset:10624
	v_lshlrev_b32_e32 v109, 16, v105
	v_lshlrev_b32_e32 v108, 16, v104
	v_and_b32_e32 v105, 0xffff0000, v105
	v_and_b32_e32 v104, 0xffff0000, v104
	s_waitcnt lgkmcnt(0)
	v_pk_add_f32 v[108:109], v[108:109], v[88:89] op_sel_hi:[1,0] neg_lo:[0,1] neg_hi:[0,1]
	v_pk_add_f32 v[104:105], v[104:105], v[88:89] op_sel_hi:[1,0] neg_lo:[0,1] neg_hi:[0,1]
	v_pk_mul_f32 v[108:109], v[88:89], v[108:109] op_sel:[1,0]
	v_pk_mul_f32 v[104:105], v[88:89], v[104:105] op_sel:[1,0]
	v_pk_mul_f32 v[108:109], v[116:117], v[108:109]
	v_pk_mul_f32 v[104:105], v[94:95], v[104:105]
	v_and_b32_sdwa v111, v109, v245 dst_sel:DWORD dst_unused:UNUSED_PAD src0_sel:WORD_1 src1_sel:DWORD
	v_and_b32_sdwa v112, v108, v245 dst_sel:DWORD dst_unused:UNUSED_PAD src0_sel:WORD_1 src1_sel:DWORD
	v_add3_u32 v108, v108, v112, s68
	v_add3_u32 v109, v109, v111, s68
	v_and_b32_sdwa v111, v105, v245 dst_sel:DWORD dst_unused:UNUSED_PAD src0_sel:WORD_1 src1_sel:DWORD
	v_and_b32_sdwa v112, v104, v245 dst_sel:DWORD dst_unused:UNUSED_PAD src0_sel:WORD_1 src1_sel:DWORD
	v_add3_u32 v105, v105, v111, s68
	v_add3_u32 v104, v104, v112, s68
	v_and_b32_e32 v105, 0xffff0000, v105
	v_and_b32_e32 v104, 0xffff0000, v104
	v_or_b32_sdwa v105, v105, v109 dst_sel:DWORD dst_unused:UNUSED_PAD src0_sel:DWORD src1_sel:WORD_1
	v_or_b32_sdwa v104, v104, v108 dst_sel:DWORD dst_unused:UNUSED_PAD src0_sel:DWORD src1_sel:WORD_1
	v_lshlrev_b32_e32 v109, 16, v107
	v_lshlrev_b32_e32 v108, 16, v106
	v_pk_add_f32 v[108:109], v[108:109], v[88:89] op_sel_hi:[1,0] neg_lo:[0,1] neg_hi:[0,1]
	v_and_b32_e32 v107, 0xffff0000, v107
	v_and_b32_e32 v106, 0xffff0000, v106
	v_pk_mul_f32 v[108:109], v[88:89], v[108:109] op_sel:[1,0]
	v_pk_add_f32 v[106:107], v[106:107], v[88:89] op_sel_hi:[1,0] neg_lo:[0,1] neg_hi:[0,1]
	v_pk_mul_f32 v[108:109], v[92:93], v[108:109]
	v_pk_mul_f32 v[88:89], v[88:89], v[106:107] op_sel:[1,0]
	v_and_b32_sdwa v106, v109, v245 dst_sel:DWORD dst_unused:UNUSED_PAD src0_sel:WORD_1 src1_sel:DWORD
	v_pk_mul_f32 v[88:89], v[90:91], v[88:89]
	v_and_b32_sdwa v107, v108, v245 dst_sel:DWORD dst_unused:UNUSED_PAD src0_sel:WORD_1 src1_sel:DWORD
	v_add3_u32 v107, v108, v107, s68
	v_add3_u32 v106, v109, v106, s68
	v_and_b32_sdwa v108, v89, v245 dst_sel:DWORD dst_unused:UNUSED_PAD src0_sel:WORD_1 src1_sel:DWORD
	v_and_b32_sdwa v109, v88, v245 dst_sel:DWORD dst_unused:UNUSED_PAD src0_sel:WORD_1 src1_sel:DWORD
	v_add3_u32 v89, v89, v108, s68
	v_add3_u32 v88, v88, v109, s68
	v_and_b32_e32 v89, 0xffff0000, v89
	v_and_b32_e32 v88, 0xffff0000, v88
	v_or_b32_sdwa v89, v89, v106 dst_sel:DWORD dst_unused:UNUSED_PAD src0_sel:DWORD src1_sel:WORD_1
	v_or_b32_sdwa v88, v88, v107 dst_sel:DWORD dst_unused:UNUSED_PAD src0_sel:DWORD src1_sel:WORD_1
	ds_write2_b64 v110, v[104:105], v[88:89] offset0:224 offset1:228
	ds_read_b64 v[104:105], v218 offset:10752
	v_lshlrev_b32_e32 v89, 16, v101
	v_lshlrev_b32_e32 v88, 16, v100
	v_and_b32_e32 v101, 0xffff0000, v101
	v_and_b32_e32 v100, 0xffff0000, v100
	s_waitcnt lgkmcnt(0)
; #define LAS __attribute__((address_space(3)))
; __device__ __forceinline__ unsigned pk2(float lo, float hi) { return f2bf(lo) | (f2bf(hi) << 16); }
; __device__ __forceinline__ float bflo(unsigned w) { return __uint_as_float(w << 16); }
; __device__ __forceinline__ float bfhi(unsigned w) { return __uint_as_float(w & 0xffff0000u); }
; __device__ __forceinline__ void sgu_item(LAS unsigned char* wl, const bf16* proj, bf16* ymix, const float* vstat, const float* sgu_g, const bf16* Wm, const float* sgu_b, int chunk, int h, int lane) {
;     ...
;         for (int i = 0; i < 8; ++i) { const int s = rsub + 16 * i; const f32x2 ms = st[s]; const v4u w = raw[i];
;             v2u lo, hi; lo.x = pk2((bflo(w.x) - ms.x) * ms.y * g0[0], (bfhi(w.x) - ms.x) * ms.y * g0[1]); lo.y = pk2((bflo(w.y) - ms.x) * ms.y * g0[2], (bfhi(w.y) - ms.x) * ms.y * g0[3]);
;             hi.x = pk2((bflo(w.z) - ms.x) * ms.y * g1[0], (bfhi(w.z) - ms.x) * ms.y * g1[1]); hi.y = pk2((bflo(w.w) - ms.x) * ms.y * g1[2], (bfhi(w.w) - ms.x) * ms.y * g1[3]);
;             *(LAS v2u*)(wl + s * VP2 + (4 * c16) * 2) = lo; *(LAS v2u*)(wl + s * VP2 + (16 + 4 * c16) * 2) = hi; }
	v_pk_add_f32 v[88:89], v[88:89], v[104:105] op_sel_hi:[1,0] neg_lo:[0,1] neg_hi:[0,1]
	v_pk_add_f32 v[100:101], v[100:101], v[104:105] op_sel_hi:[1,0] neg_lo:[0,1] neg_hi:[0,1]
	v_pk_mul_f32 v[88:89], v[104:105], v[88:89] op_sel:[1,0]
	v_pk_mul_f32 v[100:101], v[104:105], v[100:101] op_sel:[1,0]
	v_pk_mul_f32 v[88:89], v[116:117], v[88:89]
	v_pk_mul_f32 v[100:101], v[94:95], v[100:101]
	v_and_b32_sdwa v106, v89, v245 dst_sel:DWORD dst_unused:UNUSED_PAD src0_sel:WORD_1 src1_sel:DWORD
	v_and_b32_sdwa v107, v88, v245 dst_sel:DWORD dst_unused:UNUSED_PAD src0_sel:WORD_1 src1_sel:DWORD
	v_add3_u32 v88, v88, v107, s68
	v_add3_u32 v89, v89, v106, s68
	v_and_b32_sdwa v106, v101, v245 dst_sel:DWORD dst_unused:UNUSED_PAD src0_sel:WORD_1 src1_sel:DWORD
	v_and_b32_sdwa v107, v100, v245 dst_sel:DWORD dst_unused:UNUSED_PAD src0_sel:WORD_1 src1_sel:DWORD
	v_add3_u32 v101, v101, v106, s68
	v_add3_u32 v100, v100, v107, s68
	v_and_b32_e32 v101, 0xffff0000, v101
	v_and_b32_e32 v100, 0xffff0000, v100
	v_or_b32_sdwa v89, v101, v89 dst_sel:DWORD dst_unused:UNUSED_PAD src0_sel:DWORD src1_sel:WORD_1
	v_or_b32_sdwa v88, v100, v88 dst_sel:DWORD dst_unused:UNUSED_PAD src0_sel:DWORD src1_sel:WORD_1
	v_lshlrev_b32_e32 v101, 16, v103
	v_lshlrev_b32_e32 v100, 16, v102
	v_pk_add_f32 v[100:101], v[100:101], v[104:105] op_sel_hi:[1,0] neg_lo:[0,1] neg_hi:[0,1]
	v_and_b32_e32 v103, 0xffff0000, v103
	v_and_b32_e32 v102, 0xffff0000, v102
	v_pk_mul_f32 v[100:101], v[104:105], v[100:101] op_sel:[1,0]
	v_pk_add_f32 v[102:103], v[102:103], v[104:105] op_sel_hi:[1,0] neg_lo:[0,1] neg_hi:[0,1]
	v_pk_mul_f32 v[100:101], v[92:93], v[100:101]
	v_pk_mul_f32 v[102:103], v[104:105], v[102:103] op_sel:[1,0]
	v_and_b32_sdwa v104, v101, v245 dst_sel:DWORD dst_unused:UNUSED_PAD src0_sel:WORD_1 src1_sel:DWORD
	v_pk_mul_f32 v[102:103], v[90:91], v[102:103]
	v_and_b32_sdwa v105, v100, v245 dst_sel:DWORD dst_unused:UNUSED_PAD src0_sel:WORD_1 src1_sel:DWORD
	v_add3_u32 v100, v100, v105, s68
	v_add3_u32 v101, v101, v104, s68
	v_and_b32_sdwa v104, v103, v245 dst_sel:DWORD dst_unused:UNUSED_PAD src0_sel:WORD_1 src1_sel:DWORD
	v_and_b32_sdwa v105, v102, v245 dst_sel:DWORD dst_unused:UNUSED_PAD src0_sel:WORD_1 src1_sel:DWORD
	v_add3_u32 v103, v103, v104, s68
	v_add3_u32 v102, v102, v105, s68
	v_and_b32_e32 v103, 0xffff0000, v103
	v_and_b32_e32 v102, 0xffff0000, v102
	v_or_b32_sdwa v101, v103, v101 dst_sel:DWORD dst_unused:UNUSED_PAD src0_sel:DWORD src1_sel:WORD_1
	v_or_b32_sdwa v100, v102, v100 dst_sel:DWORD dst_unused:UNUSED_PAD src0_sel:DWORD src1_sel:WORD_1
	v_add_u32_e32 v102, 0x1000, v219
	ds_write2_b64 v102, v[88:89], v[100:101] offset0:128 offset1:132
	ds_read_b64 v[88:89], v218 offset:10880
	v_lshlrev_b32_e32 v101, 16, v97
	v_lshlrev_b32_e32 v100, 16, v96
	v_and_b32_e32 v97, 0xffff0000, v97
	v_and_b32_e32 v96, 0xffff0000, v96
	s_waitcnt lgkmcnt(0)
	v_pk_add_f32 v[100:101], v[100:101], v[88:89] op_sel_hi:[1,0] neg_lo:[0,1] neg_hi:[0,1]
	v_pk_add_f32 v[96:97], v[96:97], v[88:89] op_sel_hi:[1,0] neg_lo:[0,1] neg_hi:[0,1]
	v_pk_mul_f32 v[100:101], v[88:89], v[100:101] op_sel:[1,0]
	v_pk_mul_f32 v[96:97], v[88:89], v[96:97] op_sel:[1,0]
	v_pk_mul_f32 v[100:101], v[116:117], v[100:101]
	v_pk_mul_f32 v[96:97], v[94:95], v[96:97]
	v_and_b32_sdwa v102, v101, v245 dst_sel:DWORD dst_unused:UNUSED_PAD src0_sel:WORD_1 src1_sel:DWORD
	v_and_b32_sdwa v103, v100, v245 dst_sel:DWORD dst_unused:UNUSED_PAD src0_sel:WORD_1 src1_sel:DWORD
	v_add3_u32 v100, v100, v103, s68
	v_add3_u32 v101, v101, v102, s68
	v_and_b32_sdwa v102, v97, v245 dst_sel:DWORD dst_unused:UNUSED_PAD src0_sel:WORD_1 src1_sel:DWORD
	v_and_b32_sdwa v103, v96, v245 dst_sel:DWORD dst_unused:UNUSED_PAD src0_sel:WORD_1 src1_sel:DWORD
	v_add3_u32 v97, v97, v102, s68
	v_add3_u32 v96, v96, v103, s68
	v_and_b32_e32 v97, 0xffff0000, v97
	v_and_b32_e32 v96, 0xffff0000, v96
	v_or_b32_sdwa v97, v97, v101 dst_sel:DWORD dst_unused:UNUSED_PAD src0_sel:DWORD src1_sel:WORD_1
	v_or_b32_sdwa v96, v96, v100 dst_sel:DWORD dst_unused:UNUSED_PAD src0_sel:DWORD src1_sel:WORD_1
	v_lshlrev_b32_e32 v101, 16, v99
	v_lshlrev_b32_e32 v100, 16, v98
	v_pk_add_f32 v[100:101], v[100:101], v[88:89] op_sel_hi:[1,0] neg_lo:[0,1] neg_hi:[0,1]
	v_and_b32_e32 v99, 0xffff0000, v99
	v_and_b32_e32 v98, 0xffff0000, v98
	v_pk_mul_f32 v[100:101], v[88:89], v[100:101] op_sel:[1,0]
	v_pk_add_f32 v[98:99], v[98:99], v[88:89] op_sel_hi:[1,0] neg_lo:[0,1] neg_hi:[0,1]
	v_pk_mul_f32 v[100:101], v[92:93], v[100:101]
	v_pk_mul_f32 v[88:89], v[88:89], v[98:99] op_sel:[1,0]
	v_and_b32_sdwa v98, v101, v245 dst_sel:DWORD dst_unused:UNUSED_PAD src0_sel:WORD_1 src1_sel:DWORD
	v_pk_mul_f32 v[88:89], v[90:91], v[88:89]
	v_and_b32_sdwa v99, v100, v245 dst_sel:DWORD dst_unused:UNUSED_PAD src0_sel:WORD_1 src1_sel:DWORD
	v_add3_u32 v99, v100, v99, s68
	v_add3_u32 v98, v101, v98, s68
	v_and_b32_sdwa v100, v89, v245 dst_sel:DWORD dst_unused:UNUSED_PAD src0_sel:WORD_1 src1_sel:DWORD
	v_and_b32_sdwa v101, v88, v245 dst_sel:DWORD dst_unused:UNUSED_PAD src0_sel:WORD_1 src1_sel:DWORD
	v_add3_u32 v89, v89, v100, s68
	v_add3_u32 v88, v88, v101, s68
	v_and_b32_e32 v89, 0xffff0000, v89
	v_and_b32_e32 v88, 0xffff0000, v88
	v_or_b32_sdwa v89, v89, v98 dst_sel:DWORD dst_unused:UNUSED_PAD src0_sel:DWORD src1_sel:WORD_1
	v_or_b32_sdwa v88, v88, v99 dst_sel:DWORD dst_unused:UNUSED_PAD src0_sel:DWORD src1_sel:WORD_1
	v_add_u32_e32 v98, 0x1800, v219
	ds_write2_b64 v98, v[96:97], v[88:89] offset0:32 offset1:36
	ds_read_b64 v[88:89], v218 offset:11008
	v_lshlrev_b32_e32 v97, 16, v85
	v_lshlrev_b32_e32 v96, 16, v84
	v_and_b32_e32 v85, 0xffff0000, v85
	v_and_b32_e32 v84, 0xffff0000, v84
	s_waitcnt lgkmcnt(0)
; #define LAS __attribute__((address_space(3)))
; __device__ __forceinline__ unsigned pk2(float lo, float hi) { return f2bf(lo) | (f2bf(hi) << 16); }
; __device__ __forceinline__ float bflo(unsigned w) { return __uint_as_float(w << 16); }
; __device__ __forceinline__ float bfhi(unsigned w) { return __uint_as_float(w & 0xffff0000u); }
; __device__ __forceinline__ void sgu_item(LAS unsigned char* wl, const bf16* proj, bf16* ymix, const float* vstat, const float* sgu_g, const bf16* Wm, const float* sgu_b, int chunk, int h, int lane) {
;     ...
;         for (int i = 0; i < 8; ++i) { const int s = rsub + 16 * i; const f32x2 ms = st[s]; const v4u w = raw[i];
;             v2u lo, hi; lo.x = pk2((bflo(w.x) - ms.x) * ms.y * g0[0], (bfhi(w.x) - ms.x) * ms.y * g0[1]); lo.y = pk2((bflo(w.y) - ms.x) * ms.y * g0[2], (bfhi(w.y) - ms.x) * ms.y * g0[3]);
;             hi.x = pk2((bflo(w.z) - ms.x) * ms.y * g1[0], (bfhi(w.z) - ms.x) * ms.y * g1[1]); hi.y = pk2((bflo(w.w) - ms.x) * ms.y * g1[2], (bfhi(w.w) - ms.x) * ms.y * g1[3]);
;             *(LAS v2u*)(wl + s * VP2 + (4 * c16) * 2) = lo; *(LAS v2u*)(wl + s * VP2 + (16 + 4 * c16) * 2) = hi; }
;         v4u uu8[8];
; #pragma unroll
;         for (int tb = 0; tb < 8; ++tb) uu8[tb] = __builtin_nontemporal_load((const v4u*)(proj + (R0 + 16 * tb + r) * DIN + 512 + colv + 8 * q));
	v_pk_add_f32 v[96:97], v[96:97], v[88:89] op_sel_hi:[1,0] neg_lo:[0,1] neg_hi:[0,1]
	v_pk_add_f32 v[84:85], v[84:85], v[88:89] op_sel_hi:[1,0] neg_lo:[0,1] neg_hi:[0,1]
	v_pk_mul_f32 v[96:97], v[88:89], v[96:97] op_sel:[1,0]
	v_pk_mul_f32 v[84:85], v[88:89], v[84:85] op_sel:[1,0]
	v_pk_mul_f32 v[96:97], v[116:117], v[96:97]
	v_pk_mul_f32 v[84:85], v[94:95], v[84:85]
	v_and_b32_sdwa v99, v97, v245 dst_sel:DWORD dst_unused:UNUSED_PAD src0_sel:WORD_1 src1_sel:DWORD
	v_and_b32_sdwa v100, v96, v245 dst_sel:DWORD dst_unused:UNUSED_PAD src0_sel:WORD_1 src1_sel:DWORD
	v_add3_u32 v96, v96, v100, s68
	v_add3_u32 v97, v97, v99, s68
	v_and_b32_sdwa v99, v85, v245 dst_sel:DWORD dst_unused:UNUSED_PAD src0_sel:WORD_1 src1_sel:DWORD
	v_and_b32_sdwa v100, v84, v245 dst_sel:DWORD dst_unused:UNUSED_PAD src0_sel:WORD_1 src1_sel:DWORD
	v_add3_u32 v85, v85, v99, s68
	v_add3_u32 v84, v84, v100, s68
	v_and_b32_e32 v85, 0xffff0000, v85
	v_and_b32_e32 v84, 0xffff0000, v84
	v_or_b32_sdwa v85, v85, v97 dst_sel:DWORD dst_unused:UNUSED_PAD src0_sel:DWORD src1_sel:WORD_1
	v_or_b32_sdwa v84, v84, v96 dst_sel:DWORD dst_unused:UNUSED_PAD src0_sel:DWORD src1_sel:WORD_1
	v_lshlrev_b32_e32 v97, 16, v87
	v_lshlrev_b32_e32 v96, 16, v86
	v_pk_add_f32 v[96:97], v[96:97], v[88:89] op_sel_hi:[1,0] neg_lo:[0,1] neg_hi:[0,1]
	v_and_b32_e32 v87, 0xffff0000, v87
	v_and_b32_e32 v86, 0xffff0000, v86
	v_pk_mul_f32 v[96:97], v[88:89], v[96:97] op_sel:[1,0]
	v_pk_add_f32 v[86:87], v[86:87], v[88:89] op_sel_hi:[1,0] neg_lo:[0,1] neg_hi:[0,1]
	v_pk_mul_f32 v[96:97], v[92:93], v[96:97]
	v_pk_mul_f32 v[86:87], v[88:89], v[86:87] op_sel:[1,0]
	v_and_b32_sdwa v88, v97, v245 dst_sel:DWORD dst_unused:UNUSED_PAD src0_sel:WORD_1 src1_sel:DWORD
	v_pk_mul_f32 v[86:87], v[90:91], v[86:87]
	v_and_b32_sdwa v89, v96, v245 dst_sel:DWORD dst_unused:UNUSED_PAD src0_sel:WORD_1 src1_sel:DWORD
	v_add3_u32 v89, v96, v89, s68
	v_add3_u32 v88, v97, v88, s68
	v_and_b32_sdwa v96, v87, v245 dst_sel:DWORD dst_unused:UNUSED_PAD src0_sel:WORD_1 src1_sel:DWORD
	v_and_b32_sdwa v97, v86, v245 dst_sel:DWORD dst_unused:UNUSED_PAD src0_sel:WORD_1 src1_sel:DWORD
	v_add3_u32 v87, v87, v96, s68
	v_add3_u32 v86, v86, v97, s68
	v_and_b32_e32 v87, 0xffff0000, v87
	v_and_b32_e32 v86, 0xffff0000, v86
	v_or_b32_sdwa v87, v87, v88 dst_sel:DWORD dst_unused:UNUSED_PAD src0_sel:DWORD src1_sel:WORD_1
	v_or_b32_sdwa v86, v86, v89 dst_sel:DWORD dst_unused:UNUSED_PAD src0_sel:DWORD src1_sel:WORD_1
	ds_write2_b64 v98, v[84:85], v[86:87] offset0:192 offset1:196
	ds_read_b64 v[84:85], v218 offset:11136
	v_lshlrev_b32_e32 v87, 16, v81
	v_lshlrev_b32_e32 v86, 16, v80
	v_and_b32_e32 v81, 0xffff0000, v81
	v_and_b32_e32 v80, 0xffff0000, v80
	s_waitcnt lgkmcnt(0)
	v_pk_add_f32 v[86:87], v[86:87], v[84:85] op_sel_hi:[1,0] neg_lo:[0,1] neg_hi:[0,1]
	v_pk_add_f32 v[80:81], v[80:81], v[84:85] op_sel_hi:[1,0] neg_lo:[0,1] neg_hi:[0,1]
	v_pk_mul_f32 v[86:87], v[84:85], v[86:87] op_sel:[1,0]
	v_pk_mul_f32 v[80:81], v[84:85], v[80:81] op_sel:[1,0]
	v_pk_mul_f32 v[86:87], v[116:117], v[86:87]
	v_pk_mul_f32 v[80:81], v[94:95], v[80:81]
	v_and_b32_sdwa v88, v87, v245 dst_sel:DWORD dst_unused:UNUSED_PAD src0_sel:WORD_1 src1_sel:DWORD
	v_and_b32_sdwa v89, v86, v245 dst_sel:DWORD dst_unused:UNUSED_PAD src0_sel:WORD_1 src1_sel:DWORD
	v_add3_u32 v86, v86, v89, s68
	v_add3_u32 v87, v87, v88, s68
	v_and_b32_sdwa v88, v81, v245 dst_sel:DWORD dst_unused:UNUSED_PAD src0_sel:WORD_1 src1_sel:DWORD
	v_and_b32_sdwa v89, v80, v245 dst_sel:DWORD dst_unused:UNUSED_PAD src0_sel:WORD_1 src1_sel:DWORD
	v_add3_u32 v81, v81, v88, s68
	v_add3_u32 v80, v80, v89, s68
	v_and_b32_e32 v81, 0xffff0000, v81
	v_and_b32_e32 v80, 0xffff0000, v80
	v_or_b32_sdwa v81, v81, v87 dst_sel:DWORD dst_unused:UNUSED_PAD src0_sel:DWORD src1_sel:WORD_1
	v_or_b32_sdwa v80, v80, v86 dst_sel:DWORD dst_unused:UNUSED_PAD src0_sel:DWORD src1_sel:WORD_1
	v_lshlrev_b32_e32 v87, 16, v83
	v_lshlrev_b32_e32 v86, 16, v82
	v_pk_add_f32 v[86:87], v[86:87], v[84:85] op_sel_hi:[1,0] neg_lo:[0,1] neg_hi:[0,1]
	v_and_b32_e32 v83, 0xffff0000, v83
	v_and_b32_e32 v82, 0xffff0000, v82
	v_pk_mul_f32 v[86:87], v[84:85], v[86:87] op_sel:[1,0]
	v_pk_add_f32 v[82:83], v[82:83], v[84:85] op_sel_hi:[1,0] neg_lo:[0,1] neg_hi:[0,1]
	v_pk_mul_f32 v[86:87], v[92:93], v[86:87]
	v_pk_mul_f32 v[82:83], v[84:85], v[82:83] op_sel:[1,0]
	v_and_b32_sdwa v84, v87, v245 dst_sel:DWORD dst_unused:UNUSED_PAD src0_sel:WORD_1 src1_sel:DWORD
	v_pk_mul_f32 v[82:83], v[90:91], v[82:83]
	v_and_b32_sdwa v85, v86, v245 dst_sel:DWORD dst_unused:UNUSED_PAD src0_sel:WORD_1 src1_sel:DWORD
	v_add3_u32 v85, v86, v85, s68
	v_add3_u32 v84, v87, v84, s68
	v_and_b32_sdwa v86, v83, v245 dst_sel:DWORD dst_unused:UNUSED_PAD src0_sel:WORD_1 src1_sel:DWORD
	v_and_b32_sdwa v87, v82, v245 dst_sel:DWORD dst_unused:UNUSED_PAD src0_sel:WORD_1 src1_sel:DWORD
	v_add3_u32 v83, v83, v86, s68
	v_add3_u32 v82, v82, v87, s68
	v_and_b32_e32 v83, 0xffff0000, v83
	v_and_b32_e32 v82, 0xffff0000, v82
	v_or_b32_sdwa v83, v83, v84 dst_sel:DWORD dst_unused:UNUSED_PAD src0_sel:DWORD src1_sel:WORD_1
	v_or_b32_sdwa v82, v82, v85 dst_sel:DWORD dst_unused:UNUSED_PAD src0_sel:DWORD src1_sel:WORD_1
	v_add_u32_e32 v84, 0x2000, v219
	ds_write2_b64 v84, v[80:81], v[82:83] offset0:96 offset1:100
	v_lshl_add_u64 v[80:81], v[188:189], 0, s[20:21]
	v_add_co_u32_e32 v82, vcc, s0, v80
	s_mov_b32 s0, 0xf10c000
	s_nop 0
	v_addc_co_u32_e32 v83, vcc, 0, v81, vcc
	global_load_dwordx4 v[104:107], v[82:83], off offset:1024 nt
	v_add_co_u32_e32 v82, vcc, s0, v80
	s_mov_b32 s0, 0xf118000
	s_nop 0
	v_addc_co_u32_e32 v83, vcc, 0, v81, vcc
	global_load_dwordx4 v[100:103], v[82:83], off offset:1024 nt
	v_add_co_u32_e32 v82, vcc, s0, v80
	s_mov_b32 s0, 0xf130000
	s_nop 0
	v_addc_co_u32_e32 v83, vcc, 0, v81, vcc
	global_load_dwordx4 v[96:99], v[82:83], off offset:1024 nt
	v_lshl_add_u64 v[82:83], v[190:191], 0, s[20:21]
	global_load_dwordx4 v[92:95], v[82:83], off nt
	v_add_co_u32_e32 v82, vcc, s0, v80
	s_mov_b32 s0, 0xf13c000
	s_nop 0
	v_addc_co_u32_e32 v83, vcc, 0, v81, vcc
	global_load_dwordx4 v[88:91], v[82:83], off offset:1024 nt
	v_add_co_u32_e32 v82, vcc, s0, v80
	s_mov_b32 s0, 0xf148000
	s_nop 0
	v_addc_co_u32_e32 v83, vcc, 0, v81, vcc
	global_load_dwordx4 v[84:87], v[82:83], off offset:1024 nt
	v_add_co_u32_e32 v80, vcc, s0, v80
	v_lshl_add_u64 v[108:109], v[186:187], 0, s[20:21]
	s_nop 0
	v_addc_co_u32_e32 v81, vcc, 0, v81, vcc
	global_load_dwordx4 v[80:83], v[80:81], off offset:1024 nt
	s_mov_b32 s0, 0x10900000
	global_load_dwordx4 v[108:111], v[108:109], off nt
	s_waitcnt lgkmcnt(0)
; #define LAS __attribute__((address_space(3)))
; #define MFMA16(a, b, c) __builtin_amdgcn_mfma_f32_16x16x32_bf16((a), (b), (c), 0, 0, 0)
; __device__ __forceinline__ unsigned pk2(float lo, float hi) { return f2bf(lo) | (f2bf(hi) << 16); }
; __device__ __forceinline__ float bflo(unsigned w) { return __uint_as_float(w << 16); }
; __device__ __forceinline__ float bfhi(unsigned w) { return __uint_as_float(w & 0xffff0000u); }
; __device__ __forceinline__ void sgu_item(LAS unsigned char* wl, const bf16* proj, bf16* ymix, const float* vstat, const float* sgu_g, const bf16* Wm, const float* sgu_b, int chunk, int h, int lane) {
;     ...
;         for (int n = 0; n < 2; ++n) {
;             f32x4 z[8];
; #pragma unroll
;             for (int tb = 0; tb < 8; ++tb) z[tb] = (f32x4){0.f, 0.f, 0.f, 0.f};
;             int f = 0;
; #pragma unroll
;             for (int ks = 0; ks < 4; ++ks) {
;                 LAS unsigned char* ad = wl + (ks * 32 + 8 * q + (r >> 2)) * VP2 + (16 * n) * 2 + 8 * (r & 3);
;                 const s16x4 lo = __builtin_bit_cast(s16x4, __builtin_amdgcn_ds_read_tr16_b64_v4i16((LAS s16x4*)ad));
;                 const s16x4 hi = __builtin_bit_cast(s16x4, __builtin_amdgcn_ds_read_tr16_b64_v4i16((LAS s16x4*)(ad + 4 * VP2)));
;                 const bf16x8 vf = __builtin_shufflevector(lo, hi, 0, 1, 2, 3, 4, 5, 6, 7);
; #pragma unroll
;                 for (int tb = 2 * ks; tb < 8; ++tb) z[tb] = MFMA16(vf, wmf[f++], z[tb]);
;             }
; #pragma unroll
;             for (int tb = 0; tb < 8; ++tb) { const v4u uu = uu8[tb]; const unsigned ux = n == 0 ? uu.x : uu.z, uy = n == 0 ? uu.y : uu.w;
;                 v2u o; o.x = pk2(bflo(ux) * (z[tb][0] + bias[tb]), bfhi(ux) * (z[tb][1] + bias[tb])); o.y = pk2(bflo(uy) * (z[tb][2] + bias[tb]), bfhi(uy) * (z[tb][3] + bias[tb]));
;                 if (n == 0) olo[tb] = o;
	ds_read_b64_tr_b16 v[116:117], v220 offset:320
	ds_read_b64_tr_b16 v[114:115], v220
	ds_read_b64_tr_b16 v[112:113], v220 offset:32
	ds_read_b64_tr_b16 v[208:209], v220 offset:2560
	ds_read_b64_tr_b16 v[210:211], v220 offset:2880
	s_waitcnt lgkmcnt(0)
	v_mfma_f32_16x16x32_bf16 v[118:121], v[114:117], v[0:3], 0
	v_mfma_f32_16x16x32_bf16 v[122:125], v[114:117], v[4:7], 0
	s_nop 6
	v_mov_b32_e32 v138, v119
	v_mov_b32_e32 v119, v120
	v_pk_add_f32 v[118:119], v[162:163], v[118:119]
	v_mfma_f32_16x16x32_bf16 v[126:129], v[114:117], v[8:11], 0
	v_mov_b32_e32 v139, v121
	v_pk_add_f32 v[138:139], v[162:163], v[138:139]
	v_mfma_f32_16x16x32_bf16 v[130:133], v[114:117], v[16:19], 0
	v_mfma_f32_16x16x32_bf16 v[134:137], v[114:117], v[24:27], 0
	v_mfma_f32_16x16x32_bf16 v[200:203], v[114:117], v[48:51], 0
	v_mfma_f32_16x16x32_bf16 v[204:207], v[114:117], v[32:35], 0
	v_mfma_f32_16x16x32_bf16 v[114:117], v[114:117], v[40:43], 0
	v_mfma_f32_16x16x32_bf16 v[126:129], v[208:211], v[12:15], v[126:129]
	v_mfma_f32_16x16x32_bf16 v[130:133], v[208:211], v[20:23], v[130:133]
	v_mfma_f32_16x16x32_bf16 v[134:137], v[208:211], v[28:31], v[134:137]
	v_mfma_f32_16x16x32_bf16 v[200:203], v[208:211], v[56:59], v[200:203]
	v_mfma_f32_16x16x32_bf16 v[204:207], v[208:211], v[36:39], v[204:207]
	v_mfma_f32_16x16x32_bf16 v[114:117], v[208:211], v[44:47], v[114:117]
	ds_read_b64_tr_b16 v[208:209], v220 offset:5120
	ds_read_b64_tr_b16 v[210:211], v220 offset:5440
	s_waitcnt lgkmcnt(0)
	v_mfma_f32_16x16x32_bf16 v[222:225], v[208:211], v[60:63], v[200:203]
	v_mfma_f32_16x16x32_bf16 v[200:203], v[208:211], v[64:67], v[204:207]
	s_nop 2
	ds_read_b64_tr_b16 v[204:205], v220 offset:7680
	ds_read_b64_tr_b16 v[206:207], v220 offset:8000
	s_waitcnt lgkmcnt(0)
	v_mfma_f32_16x16x32_bf16 v[226:229], v[204:207], v[68:71], v[200:203]
	s_waitcnt vmcnt(0)
	s_nop 1
	v_and_b32_e32 v201, 0xffff0000, v105
	v_and_b32_e32 v200, 0xffff0000, v104
	v_lshlrev_b32_e32 v105, 16, v105
	v_lshlrev_b32_e32 v104, 16, v104
	v_pk_mul_f32 v[214:215], v[118:119], v[104:105]
	v_mov_b32_e32 v104, v123
	v_mov_b32_e32 v105, v125
	v_pk_add_f32 v[104:105], v[164:165], v[104:105]
	v_and_b32_e32 v119, 0xffff0000, v101
	v_and_b32_e32 v118, 0xffff0000, v100
	v_mov_b32_e32 v123, v124
	v_mfma_f32_16x16x32_bf16 v[114:117], v[208:211], v[72:75], v[114:117]
	v_mul_f32_e64 v212, v104, v118
	v_mul_f32_e64 v213, v105, v119
	v_pk_add_f32 v[104:105], v[164:165], v[122:123]
	v_lshlrev_b32_e32 v101, 16, v101
	v_lshlrev_b32_e32 v100, 16, v100
	v_mfma_f32_16x16x32_bf16 v[134:137], v[208:211], v[52:55], v[134:137]
	v_mul_f32_e64 v210, v104, v100
	v_mul_f32_e64 v211, v105, v101
	v_mov_b32_e32 v100, v127
	v_mov_b32_e32 v101, v129
	v_pk_add_f32 v[100:101], v[166:167], v[100:101]
	v_and_b32_e32 v105, 0xffff0000, v97
	v_and_b32_e32 v104, 0xffff0000, v96
	v_mov_b32_e32 v127, v128
	v_pk_mul_f32 v[208:209], v[100:101], v[104:105]
	v_pk_add_f32 v[100:101], v[166:167], v[126:127]
	v_lshlrev_b32_e32 v97, 16, v97
	v_lshlrev_b32_e32 v96, 16, v96
	v_mfma_f32_16x16x32_bf16 v[114:117], v[204:207], v[76:79], v[114:117]
	v_mul_f32_e64 v206, v100, v96
	v_mul_f32_e64 v207, v101, v97
	v_mov_b32_e32 v96, v131
	v_mov_b32_e32 v97, v133
	v_pk_add_f32 v[96:97], v[168:169], v[96:97]
	v_and_b32_e32 v101, 0xffff0000, v93
	v_and_b32_e32 v100, 0xffff0000, v92
	v_mov_b32_e32 v131, v132
	v_pk_mul_f32 v[204:205], v[96:97], v[100:101]
	v_pk_add_f32 v[96:97], v[168:169], v[130:131]
	v_lshlrev_b32_e32 v93, 16, v93
	v_lshlrev_b32_e32 v92, 16, v92
	v_pk_mul_f32 v[202:203], v[96:97], v[92:93]
	v_mov_b32_e32 v92, v135
	v_mov_b32_e32 v93, v137
	v_pk_add_f32 v[92:93], v[170:171], v[92:93]
	v_and_b32_e32 v97, 0xffff0000, v89
	v_and_b32_e32 v96, 0xffff0000, v88
	v_mov_b32_e32 v135, v136
	v_pk_mul_f32 v[216:217], v[138:139], v[200:201]
	v_pk_mul_f32 v[200:201], v[92:93], v[96:97]
	v_pk_add_f32 v[92:93], v[170:171], v[134:135]
	v_lshlrev_b32_e32 v89, 16, v89
	v_lshlrev_b32_e32 v88, 16, v88
	v_pk_mul_f32 v[104:105], v[92:93], v[88:89]
	v_mov_b32_e32 v88, v223
	v_mov_b32_e32 v89, v225
	v_pk_add_f32 v[88:89], v[172:173], v[88:89]
	v_and_b32_e32 v93, 0xffff0000, v85
	v_and_b32_e32 v92, 0xffff0000, v84
	v_mov_b32_e32 v223, v224
	v_pk_mul_f32 v[100:101], v[88:89], v[92:93]
	v_pk_add_f32 v[88:89], v[172:173], v[222:223]
	v_lshlrev_b32_e32 v85, 16, v85
	v_lshlrev_b32_e32 v84, 16, v84
	v_pk_mul_f32 v[96:97], v[88:89], v[84:85]
	v_mov_b32_e32 v84, v227
	v_mov_b32_e32 v85, v229
	v_pk_add_f32 v[84:85], v[174:175], v[84:85]
	v_and_b32_e32 v89, 0xffff0000, v81
	v_and_b32_e32 v88, 0xffff0000, v80
	v_mov_b32_e32 v227, v228
	v_pk_mul_f32 v[92:93], v[84:85], v[88:89]
	v_pk_add_f32 v[84:85], v[174:175], v[226:227]
	v_lshlrev_b32_e32 v81, 16, v81
	v_lshlrev_b32_e32 v80, 16, v80
	v_pk_mul_f32 v[80:81], v[84:85], v[80:81]
	v_mov_b32_e32 v84, v115
	v_mov_b32_e32 v85, v117
	v_pk_add_f32 v[84:85], v[176:177], v[84:85]
	v_and_b32_e32 v89, 0xffff0000, v109
	v_and_b32_e32 v88, 0xffff0000, v108
	v_mov_b32_e32 v115, v116
	v_pk_mul_f32 v[88:89], v[84:85], v[88:89]
	v_pk_add_f32 v[84:85], v[176:177], v[114:115]
	ds_read_b64_tr_b16 v[114:115], v220 offset:352
	ds_read_b64_tr_b16 v[234:235], v220 offset:2592
	ds_read_b64_tr_b16 v[236:237], v220 offset:2912
	s_waitcnt lgkmcnt(2)
	v_mfma_f32_16x16x32_bf16 v[120:123], v[112:115], v[16:19], 0
	v_lshlrev_b32_e32 v109, 16, v109
	v_lshlrev_b32_e32 v108, 16, v108
	v_pk_mul_f32 v[84:85], v[84:85], v[108:109]
	v_mfma_f32_16x16x32_bf16 v[226:229], v[112:115], v[48:51], 0
	v_bfe_u32 v196, v216, 16, 1
	v_add3_u32 v196, v216, v196, s68
	v_bfe_u32 v195, v217, 16, 1
	v_mfma_f32_16x16x32_bf16 v[230:233], v[112:115], v[32:35], 0
	v_add3_u32 v195, v217, v195, s68
	v_mfma_f32_16x16x32_bf16 v[116:119], v[112:115], v[8:11], 0
	v_mfma_f32_16x16x32_bf16 v[124:127], v[112:115], v[24:27], 0
	v_mfma_f32_16x16x32_bf16 v[222:225], v[112:115], v[0:3], 0
	v_mfma_f32_16x16x32_bf16 v[132:135], v[112:115], v[4:7], 0
	v_mfma_f32_16x16x32_bf16 v[112:115], v[112:115], v[40:43], 0
	s_nop 5
	v_mov_b32_e32 v108, v223
	v_mov_b32_e32 v223, v224
	v_mov_b32_e32 v109, v225
	s_waitcnt lgkmcnt(0)
; #define LAS __attribute__((address_space(3)))
; #define MFMA16(a, b, c) __builtin_amdgcn_mfma_f32_16x16x32_bf16((a), (b), (c), 0, 0, 0)
; __device__ __forceinline__ unsigned pk2(float lo, float hi) { return f2bf(lo) | (f2bf(hi) << 16); }
; __device__ __forceinline__ float bflo(unsigned w) { return __uint_as_float(w << 16); }
; __device__ __forceinline__ float bfhi(unsigned w) { return __uint_as_float(w & 0xffff0000u); }
; __device__ __forceinline__ void sgu_item(LAS unsigned char* wl, const bf16* proj, bf16* ymix, const float* vstat, const float* sgu_g, const bf16* Wm, const float* sgu_b, int chunk, int h, int lane) {
;     ...
; #pragma unroll
;             for (int ks = 0; ks < 4; ++ks) {
;                 LAS unsigned char* ad = wl + (ks * 32 + 8 * q + (r >> 2)) * VP2 + (16 * n) * 2 + 8 * (r & 3);
;                 const s16x4 lo = __builtin_bit_cast(s16x4, __builtin_amdgcn_ds_read_tr16_b64_v4i16((LAS s16x4*)ad));
;                 const s16x4 hi = __builtin_bit_cast(s16x4, __builtin_amdgcn_ds_read_tr16_b64_v4i16((LAS s16x4*)(ad + 4 * VP2)));
;                 const bf16x8 vf = __builtin_shufflevector(lo, hi, 0, 1, 2, 3, 4, 5, 6, 7);
; #pragma unroll
;                 for (int tb = 2 * ks; tb < 8; ++tb) z[tb] = MFMA16(vf, wmf[f++], z[tb]);
;             }
; #pragma unroll
;             for (int tb = 0; tb < 8; ++tb) { const v4u uu = uu8[tb]; const unsigned ux = n == 0 ? uu.x : uu.z, uy = n == 0 ? uu.y : uu.w;
;                 v2u o; o.x = pk2(bflo(ux) * (z[tb][0] + bias[tb]), bfhi(ux) * (z[tb][1] + bias[tb])); o.y = pk2(bflo(uy) * (z[tb][2] + bias[tb]), bfhi(uy) * (z[tb][3] + bias[tb]));
;                 if (n == 0) olo[tb] = o;
;                 else { v4u w; w.x = olo[tb].x; w.y = olo[tb].y; w.z = o.x; w.w = o.y; *(v4u*)(ymix + (R0 + 16 * tb + r) * D + 512 + colv + 8 * q) = w; } }
	v_mfma_f32_16x16x32_bf16 v[128:131], v[234:237], v[20:23], v[120:123]
	v_add_f32_e64 v222, v162, v222
	v_add_f32_e64 v223, v163, v223
	v_pk_add_f32 v[108:109], v[162:163], v[108:109]
	v_mfma_f32_16x16x32_bf16 v[120:123], v[234:237], v[56:59], v[226:229]
	v_mfma_f32_16x16x32_bf16 v[226:229], v[234:237], v[36:39], v[230:233]
	s_nop 2
	ds_read_b64_tr_b16 v[230:231], v220 offset:5152
	ds_read_b64_tr_b16 v[232:233], v220 offset:5472
	v_mfma_f32_16x16x32_bf16 v[136:139], v[234:237], v[12:15], v[116:119]
	v_mfma_f32_16x16x32_bf16 v[116:119], v[234:237], v[28:31], v[124:127]
	v_mfma_f32_16x16x32_bf16 v[112:115], v[234:237], v[44:47], v[112:115]
	s_waitcnt lgkmcnt(0)
	v_mfma_f32_16x16x32_bf16 v[124:127], v[230:233], v[52:55], v[116:119]
	v_mfma_f32_16x16x32_bf16 v[116:119], v[230:233], v[64:67], v[226:229]
	s_nop 2
	ds_read_b64_tr_b16 v[226:227], v220 offset:7712
	ds_read_b64_tr_b16 v[228:229], v220 offset:8032
	v_mfma_f32_16x16x32_bf16 v[112:115], v[230:233], v[72:75], v[112:115]
	s_waitcnt lgkmcnt(0)
	v_mfma_f32_16x16x32_bf16 v[116:119], v[226:229], v[68:71], v[116:119]
	v_mfma_f32_16x16x32_bf16 v[112:115], v[226:229], v[76:79], v[112:115]
	v_and_b32_e32 v227, 0xffff0000, v107
	v_and_b32_e32 v226, 0xffff0000, v106
	v_lshlrev_b32_e32 v107, 16, v107
	v_lshlrev_b32_e32 v106, 16, v106
	v_pk_mul_f32 v[106:107], v[222:223], v[106:107]
	v_pk_mul_f32 v[108:109], v[108:109], v[226:227]
	v_bfe_u32 v197, v106, 16, 1
	v_bfe_u32 v216, v107, 16, 1
	v_bfe_u32 v192, v109, 16, 1
	v_bfe_u32 v194, v108, 16, 1
	v_add3_u32 v107, v107, v216, s68
	v_add3_u32 v106, v106, v197, s68
	v_add3_u32 v108, v108, v194, s68
	v_add3_u32 v109, v109, v192, s68
	v_bfe_u32 v192, v214, 16, 1
	v_bfe_u32 v194, v215, 16, 1
	v_lshrrev_b32_e32 v106, 16, v106
	v_lshrrev_b32_e32 v107, 16, v107
	v_add3_u32 v194, v215, v194, s68
	v_add3_u32 v192, v214, v192, s68
	v_and_or_b32 v217, v109, s37, v107
	v_and_or_b32 v216, v108, s37, v106
	v_lshl_add_u64 v[106:107], v[182:183], 0, s[20:21]
	v_lshrrev_b32_e32 v192, 16, v192
	v_lshrrev_b32_e32 v194, 16, v194
	v_add_co_u32_e32 v108, vcc, s0, v106
	v_and_or_b32 v215, v195, s37, v194
	v_and_or_b32 v214, v196, s37, v192
	v_addc_co_u32_e32 v109, vcc, 0, v107, vcc
	global_store_dwordx4 v[108:109], v[214:217], off offset:1024 nt
	v_mov_b32_e32 v108, v133
	v_mov_b32_e32 v109, v135
	v_mov_b32_e32 v133, v134
	v_pk_add_f32 v[108:109], v[164:165], v[108:109]
	v_and_b32_e32 v215, 0xffff0000, v103
	v_and_b32_e32 v214, 0xffff0000, v102
	v_pk_add_f32 v[132:133], v[164:165], v[132:133]
	v_lshlrev_b32_e32 v103, 16, v103
	v_lshlrev_b32_e32 v102, 16, v102
	v_pk_mul_f32 v[108:109], v[108:109], v[214:215]
	v_pk_mul_f32 v[102:103], v[132:133], v[102:103]
	v_bfe_u32 v134, v213, 16, 1
	v_bfe_u32 v132, v109, 16, 1
	v_bfe_u32 v133, v108, 16, 1
	v_bfe_u32 v135, v212, 16, 1
	v_add3_u32 v194, v213, v134, s68
	v_bfe_u32 v134, v102, 16, 1
	v_add3_u32 v192, v212, v135, s68
	v_add3_u32 v108, v108, v133, s68
	v_add3_u32 v109, v109, v132, s68
	v_bfe_u32 v132, v210, 16, 1
	v_bfe_u32 v133, v211, 16, 1
	v_bfe_u32 v135, v103, 16, 1
	v_add3_u32 v102, v102, v134, s68
	v_add3_u32 v103, v103, v135, s68
	v_add3_u32 v133, v211, v133, s68
	v_add3_u32 v132, v210, v132, s68
	v_lshrrev_b32_e32 v102, 16, v102
	s_mov_b32 s0, 0x10908000
	v_lshrrev_b32_e32 v132, 16, v132
	v_lshrrev_b32_e32 v133, 16, v133
	v_lshrrev_b32_e32 v103, 16, v103
	v_and_or_b32 v134, v108, s37, v102
	v_add_co_u32_e32 v102, vcc, s0, v106
	v_and_or_b32 v135, v109, s37, v103
	v_and_or_b32 v133, v194, s37, v133
	v_and_or_b32 v132, v192, s37, v132
	v_addc_co_u32_e32 v103, vcc, 0, v107, vcc
	global_store_dwordx4 v[102:103], v[132:135], off offset:1024 nt
	v_mov_b32_e32 v102, v137
	v_mov_b32_e32 v103, v139
	v_pk_add_f32 v[102:103], v[166:167], v[102:103]
	v_and_b32_e32 v109, 0xffff0000, v99
	v_and_b32_e32 v108, 0xffff0000, v98
	v_mov_b32_e32 v137, v138
	v_pk_mul_f32 v[102:103], v[102:103], v[108:109]
	v_pk_add_f32 v[108:109], v[166:167], v[136:137]
	v_lshlrev_b32_e32 v99, 16, v99
	v_lshlrev_b32_e32 v98, 16, v98
	v_pk_mul_f32 v[98:99], v[108:109], v[98:99]
	v_bfe_u32 v133, v208, 16, 1
	v_bfe_u32 v108, v103, 16, 1
	v_bfe_u32 v109, v102, 16, 1
	v_add3_u32 v136, v208, v133, s68
	v_bfe_u32 v133, v98, 16, 1
	v_add3_u32 v102, v102, v109, s68
	v_add3_u32 v103, v103, v108, s68
	v_bfe_u32 v108, v206, 16, 1
	v_bfe_u32 v109, v207, 16, 1
	v_bfe_u32 v134, v99, 16, 1
	v_add3_u32 v98, v98, v133, s68
	v_bfe_u32 v132, v209, 16, 1
	v_add3_u32 v99, v99, v134, s68
	v_add3_u32 v109, v207, v109, s68
	v_add3_u32 v108, v206, v108, s68
	v_lshrrev_b32_e32 v98, 16, v98
	s_mov_b32 s0, 0x10910000
	v_add3_u32 v132, v209, v132, s68
	v_lshrrev_b32_e32 v108, 16, v108
	v_lshrrev_b32_e32 v109, 16, v109
	v_lshrrev_b32_e32 v99, 16, v99
	v_and_or_b32 v134, v102, s37, v98
	v_add_co_u32_e32 v98, vcc, s0, v106
	v_and_or_b32 v135, v103, s37, v99
	v_and_or_b32 v133, v132, s37, v109
	v_and_or_b32 v132, v136, s37, v108
	v_addc_co_u32_e32 v99, vcc, 0, v107, vcc
	global_store_dwordx4 v[98:99], v[132:135], off offset:1024 nt
	v_mov_b32_e32 v98, v129
	v_mov_b32_e32 v99, v131
	v_pk_add_f32 v[98:99], v[168:169], v[98:99]
	v_and_b32_e32 v103, 0xffff0000, v95
	v_and_b32_e32 v102, 0xffff0000, v94
	v_mov_b32_e32 v129, v130
	v_pk_mul_f32 v[98:99], v[98:99], v[102:103]
	v_pk_add_f32 v[102:103], v[168:169], v[128:129]
	v_lshlrev_b32_e32 v95, 16, v95
	v_lshlrev_b32_e32 v94, 16, v94
	v_pk_mul_f32 v[94:95], v[102:103], v[94:95]
	v_bfe_u32 v102, v99, 16, 1
	v_bfe_u32 v103, v98, 16, 1
	v_add3_u32 v98, v98, v103, s68
	v_add3_u32 v99, v99, v102, s68
	v_bfe_u32 v102, v202, 16, 1
	v_bfe_u32 v103, v203, 16, 1
	v_bfe_u32 v128, v94, 16, 1
	v_bfe_u32 v129, v95, 16, 1
	v_bfe_u32 v108, v205, 16, 1
; __device__ __forceinline__ unsigned pk2(float lo, float hi) { return f2bf(lo) | (f2bf(hi) << 16); }
; __device__ __forceinline__ float bflo(unsigned w) { return __uint_as_float(w << 16); }
; __device__ __forceinline__ float bfhi(unsigned w) { return __uint_as_float(w & 0xffff0000u); }
; #define LDS_WAIT() asm volatile("s_waitcnt lgkmcnt(0)" ::: "memory")
; __device__ __forceinline__ void sgu_item(LAS unsigned char* wl, const bf16* proj, bf16* ymix, const float* vstat, const float* sgu_g, const bf16* Wm, const float* sgu_b, int chunk, int h, int lane) {
;     ...
;             for (int tb = 0; tb < 8; ++tb) { const v4u uu = uu8[tb]; const unsigned ux = n == 0 ? uu.x : uu.z, uy = n == 0 ? uu.y : uu.w;
;                 v2u o; o.x = pk2(bflo(ux) * (z[tb][0] + bias[tb]), bfhi(ux) * (z[tb][1] + bias[tb])); o.y = pk2(bflo(uy) * (z[tb][2] + bias[tb]), bfhi(uy) * (z[tb][3] + bias[tb]));
;                 if (n == 0) olo[tb] = o;
;                 else { v4u w; w.x = olo[tb].x; w.y = olo[tb].y; w.z = o.x; w.w = o.y; *(v4u*)(ymix + (R0 + 16 * tb + r) * D + 512 + colv + 8 * q) = w; } }
;         }
;         LDS_WAIT();
	v_bfe_u32 v109, v204, 16, 1
	v_add3_u32 v95, v95, v129, s68
	v_add3_u32 v94, v94, v128, s68
	v_add3_u32 v103, v203, v103, s68
	v_add3_u32 v102, v202, v102, s68
	v_add3_u32 v109, v204, v109, s68
	v_add3_u32 v108, v205, v108, s68
	v_lshrrev_b32_e32 v102, 16, v102
	v_lshrrev_b32_e32 v103, 16, v103
	v_lshrrev_b32_e32 v94, 16, v94
	v_lshrrev_b32_e32 v95, 16, v95
	v_and_or_b32 v131, v99, s37, v95
	v_and_or_b32 v130, v98, s37, v94
	v_and_or_b32 v129, v108, s37, v103
	v_and_or_b32 v128, v109, s37, v102
	v_lshl_add_u64 v[94:95], v[184:185], 0, s[20:21]
	global_store_dwordx4 v[94:95], v[128:131], off nt
	v_mov_b32_e32 v94, v125
	v_mov_b32_e32 v95, v127
	v_pk_add_f32 v[94:95], v[170:171], v[94:95]
	v_and_b32_e32 v99, 0xffff0000, v91
	v_and_b32_e32 v98, 0xffff0000, v90
	v_mov_b32_e32 v125, v126
	v_pk_mul_f32 v[94:95], v[94:95], v[98:99]
	v_pk_add_f32 v[98:99], v[170:171], v[124:125]
	v_lshlrev_b32_e32 v91, 16, v91
	v_lshlrev_b32_e32 v90, 16, v90
	v_pk_mul_f32 v[90:91], v[98:99], v[90:91]
	v_bfe_u32 v103, v200, 16, 1
	v_bfe_u32 v98, v95, 16, 1
	v_bfe_u32 v99, v94, 16, 1
	v_add3_u32 v108, v200, v103, s68
	v_bfe_u32 v103, v90, 16, 1
	v_mfma_f32_16x16x32_bf16 v[120:123], v[230:233], v[60:63], v[120:123]
	v_add3_u32 v94, v94, v99, s68
	v_add3_u32 v95, v95, v98, s68
	v_bfe_u32 v98, v104, 16, 1
	v_bfe_u32 v99, v105, 16, 1
	v_bfe_u32 v109, v91, 16, 1
	v_add3_u32 v90, v90, v103, s68
	v_bfe_u32 v102, v201, 16, 1
	v_add3_u32 v91, v91, v109, s68
	v_add3_u32 v99, v105, v99, s68
	v_add3_u32 v98, v104, v98, s68
	v_lshrrev_b32_e32 v90, 16, v90
	s_mov_b32 s0, 0x10920000
	v_add3_u32 v102, v201, v102, s68
	v_lshrrev_b32_e32 v98, 16, v98
	v_lshrrev_b32_e32 v99, 16, v99
	v_lshrrev_b32_e32 v91, 16, v91
	v_and_or_b32 v104, v94, s37, v90
	v_add_co_u32_e32 v90, vcc, s0, v106
	v_and_or_b32 v105, v95, s37, v91
	v_and_or_b32 v103, v102, s37, v99
	v_and_or_b32 v102, v108, s37, v98
	v_addc_co_u32_e32 v91, vcc, 0, v107, vcc
	global_store_dwordx4 v[90:91], v[102:105], off offset:1024 nt
	v_mov_b32_e32 v90, v121
	v_mov_b32_e32 v91, v123
	v_pk_add_f32 v[90:91], v[172:173], v[90:91]
	v_and_b32_e32 v95, 0xffff0000, v87
	v_and_b32_e32 v94, 0xffff0000, v86
	v_mov_b32_e32 v121, v122
	v_pk_mul_f32 v[90:91], v[90:91], v[94:95]
	v_pk_add_f32 v[94:95], v[172:173], v[120:121]
	v_lshlrev_b32_e32 v87, 16, v87
	v_lshlrev_b32_e32 v86, 16, v86
	v_pk_mul_f32 v[86:87], v[94:95], v[86:87]
	v_bfe_u32 v99, v100, 16, 1
	v_bfe_u32 v94, v91, 16, 1
	v_bfe_u32 v95, v90, 16, 1
	v_bfe_u32 v98, v101, 16, 1
	v_add3_u32 v99, v100, v99, s68
	v_bfe_u32 v100, v86, 16, 1
	v_add3_u32 v98, v101, v98, s68
	v_add3_u32 v90, v90, v95, s68
	v_add3_u32 v91, v91, v94, s68
	v_bfe_u32 v94, v96, 16, 1
	v_bfe_u32 v95, v97, 16, 1
	v_bfe_u32 v101, v87, 16, 1
	v_add3_u32 v86, v86, v100, s68
	v_add3_u32 v87, v87, v101, s68
	v_add3_u32 v95, v97, v95, s68
	v_add3_u32 v94, v96, v94, s68
	v_lshrrev_b32_e32 v86, 16, v86
	s_mov_b32 s0, 0x10928000
	v_lshrrev_b32_e32 v94, 16, v94
	v_lshrrev_b32_e32 v95, 16, v95
	v_lshrrev_b32_e32 v87, 16, v87
	v_and_or_b32 v96, v90, s37, v86
	v_add_co_u32_e32 v86, vcc, s0, v106
	v_and_or_b32 v97, v91, s37, v87
	v_and_or_b32 v95, v98, s37, v95
	v_and_or_b32 v94, v99, s37, v94
	v_addc_co_u32_e32 v87, vcc, 0, v107, vcc
	global_store_dwordx4 v[86:87], v[94:97], off offset:1024 nt
	v_mov_b32_e32 v86, v117
	v_mov_b32_e32 v87, v119
	v_pk_add_f32 v[86:87], v[174:175], v[86:87]
	v_and_b32_e32 v91, 0xffff0000, v83
	v_and_b32_e32 v90, 0xffff0000, v82
	v_mov_b32_e32 v117, v118
	v_pk_mul_f32 v[86:87], v[86:87], v[90:91]
	v_pk_add_f32 v[90:91], v[174:175], v[116:117]
	v_lshlrev_b32_e32 v83, 16, v83
	v_lshlrev_b32_e32 v82, 16, v82
	v_pk_mul_f32 v[82:83], v[90:91], v[82:83]
	v_bfe_u32 v94, v93, 16, 1
	v_bfe_u32 v90, v87, 16, 1
	v_bfe_u32 v91, v86, 16, 1
	v_bfe_u32 v95, v92, 16, 1
	v_add3_u32 v93, v93, v94, s68
	v_bfe_u32 v94, v82, 16, 1
	v_add3_u32 v92, v92, v95, s68
	v_add3_u32 v86, v86, v91, s68
	v_add3_u32 v87, v87, v90, s68
	v_bfe_u32 v90, v80, 16, 1
	v_bfe_u32 v91, v81, 16, 1
	v_bfe_u32 v95, v83, 16, 1
	v_add3_u32 v82, v82, v94, s68
	v_add3_u32 v83, v83, v95, s68
	v_add3_u32 v81, v81, v91, s68
	v_add3_u32 v80, v80, v90, s68
	v_lshrrev_b32_e32 v82, 16, v82
	s_mov_b32 s0, 0x10930000
	v_lshrrev_b32_e32 v80, 16, v80
	v_lshrrev_b32_e32 v81, 16, v81
	v_lshrrev_b32_e32 v83, 16, v83
	v_and_or_b32 v82, v86, s37, v82
	v_add_co_u32_e32 v86, vcc, s0, v106
	v_and_or_b32 v83, v87, s37, v83
	v_and_or_b32 v81, v93, s37, v81
	v_and_or_b32 v80, v92, s37, v80
	v_addc_co_u32_e32 v87, vcc, 0, v107, vcc
	global_store_dwordx4 v[86:87], v[80:83], off offset:1024 nt
	v_lshlrev_b32_e32 v87, 16, v111
	v_lshlrev_b32_e32 v86, 16, v110
	v_mov_b32_e32 v80, v113
	v_mov_b32_e32 v81, v115
	v_pk_add_f32 v[80:81], v[176:177], v[80:81]
	v_and_b32_e32 v83, 0xffff0000, v111
	v_and_b32_e32 v82, 0xffff0000, v110
	v_mov_b32_e32 v113, v114
	v_pk_mul_f32 v[80:81], v[80:81], v[82:83]
	v_pk_add_f32 v[82:83], v[176:177], v[112:113]
	v_bfe_u32 v90, v89, 16, 1
	v_pk_mul_f32 v[82:83], v[82:83], v[86:87]
	v_bfe_u32 v86, v81, 16, 1
	v_bfe_u32 v87, v80, 16, 1
	v_bfe_u32 v91, v88, 16, 1
	v_add3_u32 v88, v88, v91, s68
	v_add3_u32 v89, v89, v90, s68
	v_add3_u32 v80, v80, v87, s68
	v_add3_u32 v81, v81, v86, s68
	v_bfe_u32 v86, v84, 16, 1
	v_bfe_u32 v87, v85, 16, 1
	v_bfe_u32 v90, v82, 16, 1
	v_bfe_u32 v91, v83, 16, 1
	v_add3_u32 v83, v83, v91, s68
	v_add3_u32 v82, v82, v90, s68
	v_add3_u32 v85, v85, v87, s68
	v_add3_u32 v84, v84, v86, s68
	v_lshrrev_b32_e32 v84, 16, v84
	v_lshrrev_b32_e32 v85, 16, v85
	v_lshrrev_b32_e32 v82, 16, v82
	v_lshrrev_b32_e32 v83, 16, v83
	v_and_or_b32 v83, v81, s37, v83
	v_and_or_b32 v82, v80, s37, v82
	v_and_or_b32 v81, v89, s37, v85
	v_and_or_b32 v80, v88, s37, v84
	v_lshl_add_u64 v[84:85], v[180:181], 0, s[20:21]
	global_store_dwordx4 v[84:85], v[80:83], off nt
	s_waitcnt lgkmcnt(0)
	s_add_u32 s20, s20, 64
	s_addc_u32 s21, s21, 0
	s_cmpk_lg_i32 s20, 0x100
	s_cbranch_scc1 .LBB0_511
	s_add_i32 s5, s5, s77
	s_add_i32 s4, s4, s7
	s_cmp_lt_i32 s5, s2
	s_cbranch_scc1 .LBB0_510
